# v11 + GEMM K-loop back-edge rotation: loop counter/pointer updates and exit compare moved in front of the loop-back barrier (8 rolled K-loops)
# baseline (speedup 1.0000x reference)
.LBB0_635:
	ds_read_b128 v[148:151], v158
	ds_read_b128 v[152:155], v158 offset:1024
	ds_read_b128 v[164:167], v158 offset:2048
	ds_read_b128 v[168:171], v158 offset:3072
	ds_read_b128 v[172:175], v159
	ds_read_b128 v[176:179], v159 offset:1024
	ds_read_b128 v[180:183], v159 offset:2048
	ds_read_b128 v[184:187], v159 offset:3072
	s_add_u32 s12, s10, 0xfffc0080
	s_addc_u32 s13, s11, -1
	s_cmp_eq_u32 s40, 12
	s_cselect_b32 s15, s3, s13
	s_cselect_b32 s14, s5, s12
	s_cselect_b32 s13, s9, s33
	s_cselect_b32 s12, s29, s31
	v_lshl_add_u64 v[220:221], s[10:11], 0, v[140:141]
	s_add_i32 m0, s47, 0xc000
	ds_read_b128 v[188:191], v160
	ds_read_b128 v[192:195], v160 offset:1024
	ds_read_b128 v[196:199], v160 offset:2048
	ds_read_b128 v[200:203], v160 offset:3072
	ds_read_b128 v[204:207], v160 offset:4096
	ds_read_b128 v[208:211], v160 offset:5120
	ds_read_b128 v[212:215], v160 offset:6144
	ds_read_b128 v[216:219], v160 offset:7168
	global_load_lds_dwordx4 v[220:221], off
	v_lshl_add_u64 v[220:221], s[10:11], 0, v[138:139]
	s_add_i32 m0, s47, 0xe000
	s_nop 0
	global_load_lds_dwordx4 v[220:221], off
	s_waitcnt vmcnt(8)
	s_waitcnt lgkmcnt(0)
	s_barrier
	s_setprio 1
	s_waitcnt lgkmcnt(0)
	v_mfma_f32_16x16x32_bf16 v[124:127], v[148:151], v[188:191], v[124:127]
	v_mfma_f32_16x16x32_bf16 v[120:123], v[164:167], v[188:191], v[120:123]
	v_mfma_f32_16x16x32_bf16 v[108:111], v[148:151], v[196:199], v[108:111]
	v_mfma_f32_16x16x32_bf16 v[104:107], v[164:167], v[196:199], v[104:107]
	v_mfma_f32_16x16x32_bf16 v[92:95], v[148:151], v[204:207], v[92:95]
	v_mfma_f32_16x16x32_bf16 v[88:91], v[164:167], v[204:207], v[88:91]
	v_mfma_f32_16x16x32_bf16 v[76:79], v[148:151], v[212:215], v[76:79]
	v_mfma_f32_16x16x32_bf16 v[72:75], v[164:167], v[212:215], v[72:75]
	v_mfma_f32_16x16x32_bf16 v[124:127], v[152:155], v[192:195], v[124:127]
	v_mfma_f32_16x16x32_bf16 v[120:123], v[168:171], v[192:195], v[120:123]
	v_mfma_f32_16x16x32_bf16 v[108:111], v[152:155], v[200:203], v[108:111]
	v_mfma_f32_16x16x32_bf16 v[104:107], v[168:171], v[200:203], v[104:107]
	v_mfma_f32_16x16x32_bf16 v[92:95], v[152:155], v[208:211], v[92:95]
	v_mfma_f32_16x16x32_bf16 v[88:91], v[168:171], v[208:211], v[88:91]
	v_mfma_f32_16x16x32_bf16 v[76:79], v[152:155], v[216:219], v[76:79]
	v_mfma_f32_16x16x32_bf16 v[72:75], v[168:171], v[216:219], v[72:75]
	s_setprio 0
	s_setprio 1
	v_mfma_f32_16x16x32_bf16 v[116:119], v[172:175], v[188:191], v[116:119]
	v_mfma_f32_16x16x32_bf16 v[112:115], v[180:183], v[188:191], v[112:115]
	v_mfma_f32_16x16x32_bf16 v[100:103], v[172:175], v[196:199], v[100:103]
	v_mfma_f32_16x16x32_bf16 v[96:99], v[180:183], v[196:199], v[96:99]
	v_mfma_f32_16x16x32_bf16 v[84:87], v[172:175], v[204:207], v[84:87]
	v_mfma_f32_16x16x32_bf16 v[80:83], v[180:183], v[204:207], v[80:83]
	v_mfma_f32_16x16x32_bf16 v[68:71], v[172:175], v[212:215], v[68:71]
	v_mfma_f32_16x16x32_bf16 v[64:67], v[180:183], v[212:215], v[64:67]
	v_mfma_f32_16x16x32_bf16 v[116:119], v[176:179], v[192:195], v[116:119]
	v_mfma_f32_16x16x32_bf16 v[112:115], v[184:187], v[192:195], v[112:115]
	v_mfma_f32_16x16x32_bf16 v[100:103], v[176:179], v[200:203], v[100:103]
	v_mfma_f32_16x16x32_bf16 v[96:99], v[184:187], v[200:203], v[96:99]
	v_mfma_f32_16x16x32_bf16 v[84:87], v[176:179], v[208:211], v[84:87]
	v_mfma_f32_16x16x32_bf16 v[80:83], v[184:187], v[208:211], v[80:83]
	v_mfma_f32_16x16x32_bf16 v[68:71], v[176:179], v[216:219], v[68:71]
	v_mfma_f32_16x16x32_bf16 v[64:67], v[184:187], v[216:219], v[64:67]
	s_setprio 0
	s_barrier
	s_add_i32 s41, s61, s46
	v_lshl_add_u64 v[220:221], s[12:13], 0, v[130:131]
	s_mov_b32 m0, s41
	ds_read_b128 v[188:191], v160 offset:16384
	ds_read_b128 v[192:195], v160 offset:17408
	ds_read_b128 v[196:199], v160 offset:18432
	ds_read_b128 v[200:203], v160 offset:19456
	ds_read_b128 v[204:207], v160 offset:20480
	ds_read_b128 v[208:211], v160 offset:21504
	ds_read_b128 v[212:215], v160 offset:22528
	ds_read_b128 v[216:219], v160 offset:23552
	global_load_lds_dwordx4 v[220:221], off
	s_add_i32 m0, s41, 0x2000
	s_add_u32 s66, s12, 0x40000
	v_lshl_add_u64 v[222:223], s[12:13], 0, v[134:135]
	s_addc_u32 s67, s13, 0
	s_add_i32 s41, s62, s46
	global_load_lds_dwordx4 v[222:223], off
	v_lshl_add_u64 v[224:225], s[66:67], 0, v[130:131]
	s_mov_b32 m0, s41
	v_lshl_add_u64 v[226:227], s[14:15], 0, v[132:133]
	global_load_lds_dwordx4 v[224:225], off
	v_lshl_add_u64 v[224:225], s[66:67], 0, v[134:135]
	s_add_i32 m0, s41, 0x2000
	s_nop 0
	global_load_lds_dwordx4 v[224:225], off
	v_lshl_add_u64 v[224:225], s[14:15], 0, v[128:129]
	s_mov_b32 m0, s47
	s_nop 0
	global_load_lds_dwordx4 v[224:225], off
	s_mov_b32 m0, s52
	s_nop 0
	global_load_lds_dwordx4 v[226:227], off
	s_waitcnt vmcnt(8)
	s_waitcnt lgkmcnt(0)
	s_barrier
	s_setprio 1
	s_waitcnt lgkmcnt(0)
	v_mfma_f32_16x16x32_bf16 v[60:63], v[148:151], v[188:191], v[60:63]
	v_mfma_f32_16x16x32_bf16 v[56:59], v[164:167], v[188:191], v[56:59]
	v_mfma_f32_16x16x32_bf16 v[44:47], v[148:151], v[196:199], v[44:47]
	v_mfma_f32_16x16x32_bf16 v[40:43], v[164:167], v[196:199], v[40:43]
	v_mfma_f32_16x16x32_bf16 v[28:31], v[148:151], v[204:207], v[28:31]
	v_mfma_f32_16x16x32_bf16 v[24:27], v[164:167], v[204:207], v[24:27]
	v_mfma_f32_16x16x32_bf16 v[12:15], v[148:151], v[212:215], v[12:15]
	v_mfma_f32_16x16x32_bf16 v[8:11], v[164:167], v[212:215], v[8:11]
	v_mfma_f32_16x16x32_bf16 v[60:63], v[152:155], v[192:195], v[60:63]
	v_mfma_f32_16x16x32_bf16 v[56:59], v[168:171], v[192:195], v[56:59]
	v_mfma_f32_16x16x32_bf16 v[44:47], v[152:155], v[200:203], v[44:47]
	v_mfma_f32_16x16x32_bf16 v[40:43], v[168:171], v[200:203], v[40:43]
	v_mfma_f32_16x16x32_bf16 v[28:31], v[152:155], v[208:211], v[28:31]
	v_mfma_f32_16x16x32_bf16 v[24:27], v[168:171], v[208:211], v[24:27]
	v_mfma_f32_16x16x32_bf16 v[12:15], v[152:155], v[216:219], v[12:15]
	v_mfma_f32_16x16x32_bf16 v[8:11], v[168:171], v[216:219], v[8:11]
	s_setprio 0
	s_setprio 1
	v_mfma_f32_16x16x32_bf16 v[52:55], v[172:175], v[188:191], v[52:55]
	v_mfma_f32_16x16x32_bf16 v[48:51], v[180:183], v[188:191], v[48:51]
	v_mfma_f32_16x16x32_bf16 v[36:39], v[172:175], v[196:199], v[36:39]
	v_mfma_f32_16x16x32_bf16 v[32:35], v[180:183], v[196:199], v[32:35]
	v_mfma_f32_16x16x32_bf16 v[20:23], v[172:175], v[204:207], v[20:23]
	v_mfma_f32_16x16x32_bf16 v[16:19], v[180:183], v[204:207], v[16:19]
	v_mfma_f32_16x16x32_bf16 v[4:7], v[172:175], v[212:215], v[4:7]
	v_mfma_f32_16x16x32_bf16 v[0:3], v[180:183], v[212:215], v[0:3]
	v_mfma_f32_16x16x32_bf16 v[52:55], v[176:179], v[192:195], v[52:55]
	v_mfma_f32_16x16x32_bf16 v[48:51], v[184:187], v[192:195], v[48:51]
	v_mfma_f32_16x16x32_bf16 v[36:39], v[176:179], v[200:203], v[36:39]
	v_mfma_f32_16x16x32_bf16 v[32:35], v[184:187], v[200:203], v[32:35]
	v_mfma_f32_16x16x32_bf16 v[20:23], v[176:179], v[208:211], v[20:23]
	v_mfma_f32_16x16x32_bf16 v[16:19], v[184:187], v[208:211], v[16:19]
	v_mfma_f32_16x16x32_bf16 v[4:7], v[176:179], v[216:219], v[4:7]
	v_mfma_f32_16x16x32_bf16 v[0:3], v[184:187], v[216:219], v[0:3]
	s_setprio 0
	s_barrier
	s_add_i32 s41, 0, 0x18000
	v_add_u32_e32 v136, s41, v156
	s_add_i32 s66, 0, 0x1c000
	ds_read_b128 v[148:151], v136
	ds_read_b128 v[152:155], v136 offset:1024
	ds_read_b128 v[164:167], v136 offset:2048
	ds_read_b128 v[168:171], v136 offset:3072
	v_add_u32_e32 v136, s66, v156
	ds_read_b128 v[172:175], v136
	ds_read_b128 v[176:179], v136 offset:1024
	ds_read_b128 v[180:183], v136 offset:2048
	ds_read_b128 v[184:187], v136 offset:3072
	s_add_u32 s14, s14, 0x40000
	s_addc_u32 s15, s15, 0
	s_mov_b32 m0, s53
	v_lshl_add_u64 v[228:229], s[14:15], 0, v[128:129]
	ds_read_b128 v[188:191], v160 offset:32768
	ds_read_b128 v[192:195], v160 offset:33792
	ds_read_b128 v[196:199], v160 offset:34816
	ds_read_b128 v[200:203], v160 offset:35840
	ds_read_b128 v[204:207], v160 offset:36864
	ds_read_b128 v[208:211], v160 offset:37888
	ds_read_b128 v[212:215], v160 offset:38912
	ds_read_b128 v[216:219], v160 offset:39936
	global_load_lds_dwordx4 v[228:229], off
	v_lshl_add_u64 v[228:229], s[14:15], 0, v[132:133]
	s_mov_b32 m0, s54
	s_nop 0
	global_load_lds_dwordx4 v[228:229], off
	s_waitcnt vmcnt(8)
	s_waitcnt lgkmcnt(0)
	s_barrier
	s_setprio 1
	s_waitcnt lgkmcnt(0)
	v_mfma_f32_16x16x32_bf16 v[124:127], v[148:151], v[188:191], v[124:127]
	v_mfma_f32_16x16x32_bf16 v[120:123], v[164:167], v[188:191], v[120:123]
	v_mfma_f32_16x16x32_bf16 v[108:111], v[148:151], v[196:199], v[108:111]
	v_mfma_f32_16x16x32_bf16 v[104:107], v[164:167], v[196:199], v[104:107]
	v_mfma_f32_16x16x32_bf16 v[92:95], v[148:151], v[204:207], v[92:95]
	v_mfma_f32_16x16x32_bf16 v[88:91], v[164:167], v[204:207], v[88:91]
	v_mfma_f32_16x16x32_bf16 v[76:79], v[148:151], v[212:215], v[76:79]
	v_mfma_f32_16x16x32_bf16 v[72:75], v[164:167], v[212:215], v[72:75]
	v_mfma_f32_16x16x32_bf16 v[124:127], v[152:155], v[192:195], v[124:127]
	v_mfma_f32_16x16x32_bf16 v[120:123], v[168:171], v[192:195], v[120:123]
	v_mfma_f32_16x16x32_bf16 v[108:111], v[152:155], v[200:203], v[108:111]
	v_mfma_f32_16x16x32_bf16 v[104:107], v[168:171], v[200:203], v[104:107]
	v_mfma_f32_16x16x32_bf16 v[92:95], v[152:155], v[208:211], v[92:95]
	v_mfma_f32_16x16x32_bf16 v[88:91], v[168:171], v[208:211], v[88:91]
	v_mfma_f32_16x16x32_bf16 v[76:79], v[152:155], v[216:219], v[76:79]
	v_mfma_f32_16x16x32_bf16 v[72:75], v[168:171], v[216:219], v[72:75]
	s_setprio 0
	s_setprio 1
	v_mfma_f32_16x16x32_bf16 v[116:119], v[172:175], v[188:191], v[116:119]
	v_mfma_f32_16x16x32_bf16 v[112:115], v[180:183], v[188:191], v[112:115]
	v_mfma_f32_16x16x32_bf16 v[100:103], v[172:175], v[196:199], v[100:103]
	v_mfma_f32_16x16x32_bf16 v[96:99], v[180:183], v[196:199], v[96:99]
	v_mfma_f32_16x16x32_bf16 v[84:87], v[172:175], v[204:207], v[84:87]
	v_mfma_f32_16x16x32_bf16 v[80:83], v[180:183], v[204:207], v[80:83]
	v_mfma_f32_16x16x32_bf16 v[68:71], v[172:175], v[212:215], v[68:71]
	v_mfma_f32_16x16x32_bf16 v[64:67], v[180:183], v[212:215], v[64:67]
	v_mfma_f32_16x16x32_bf16 v[116:119], v[176:179], v[192:195], v[116:119]
	v_mfma_f32_16x16x32_bf16 v[112:115], v[184:187], v[192:195], v[112:115]
	v_mfma_f32_16x16x32_bf16 v[100:103], v[176:179], v[200:203], v[100:103]
	v_mfma_f32_16x16x32_bf16 v[96:99], v[184:187], v[200:203], v[96:99]
	v_mfma_f32_16x16x32_bf16 v[84:87], v[176:179], v[208:211], v[84:87]
	v_mfma_f32_16x16x32_bf16 v[80:83], v[184:187], v[208:211], v[80:83]
	v_mfma_f32_16x16x32_bf16 v[68:71], v[176:179], v[216:219], v[68:71]
	v_mfma_f32_16x16x32_bf16 v[64:67], v[184:187], v[216:219], v[64:67]
	s_setprio 0
	s_barrier
	s_add_i32 s14, s41, s46
	v_lshl_add_u64 v[220:221], v[220:221], 0, s[24:25]
	s_mov_b32 m0, s14
	ds_read_b128 v[188:191], v160 offset:49152
	ds_read_b128 v[192:195], v160 offset:50176
	ds_read_b128 v[196:199], v160 offset:51200
	ds_read_b128 v[200:203], v160 offset:52224
	ds_read_b128 v[204:207], v160 offset:53248
	ds_read_b128 v[208:211], v160 offset:54272
	ds_read_b128 v[212:215], v160 offset:55296
	ds_read_b128 v[216:219], v160 offset:56320
	global_load_lds_dwordx4 v[220:221], off
	s_add_i32 m0, s14, 0x2000
	s_add_u32 s12, s12, 0x40080
	v_lshl_add_u64 v[220:221], v[222:223], 0, s[24:25]
	s_addc_u32 s13, s13, 0
	s_add_i32 s14, s66, s46
	global_load_lds_dwordx4 v[220:221], off
	v_lshl_add_u64 v[220:221], s[12:13], 0, v[130:131]
	s_mov_b32 m0, s14
	s_nop 0
	global_load_lds_dwordx4 v[220:221], off
	v_lshl_add_u64 v[220:221], s[12:13], 0, v[134:135]
	s_add_i32 m0, s14, 0x2000
	s_nop 0
	global_load_lds_dwordx4 v[220:221], off
	v_lshl_add_u64 v[220:221], v[224:225], 0, s[24:25]
	s_mov_b32 m0, s56
	s_nop 0
	global_load_lds_dwordx4 v[220:221], off
	v_lshl_add_u64 v[220:221], v[226:227], 0, s[24:25]
	s_mov_b32 m0, s57
	s_nop 0
	global_load_lds_dwordx4 v[220:221], off
	s_waitcnt vmcnt(8)
	s_waitcnt lgkmcnt(0)
	s_barrier
	s_setprio 1
	s_waitcnt lgkmcnt(0)
	v_mfma_f32_16x16x32_bf16 v[60:63], v[148:151], v[188:191], v[60:63]
	v_mfma_f32_16x16x32_bf16 v[56:59], v[164:167], v[188:191], v[56:59]
	v_mfma_f32_16x16x32_bf16 v[44:47], v[148:151], v[196:199], v[44:47]
	v_mfma_f32_16x16x32_bf16 v[40:43], v[164:167], v[196:199], v[40:43]
	v_mfma_f32_16x16x32_bf16 v[28:31], v[148:151], v[204:207], v[28:31]
	v_mfma_f32_16x16x32_bf16 v[24:27], v[164:167], v[204:207], v[24:27]
	v_mfma_f32_16x16x32_bf16 v[12:15], v[148:151], v[212:215], v[12:15]
	v_mfma_f32_16x16x32_bf16 v[8:11], v[164:167], v[212:215], v[8:11]
	v_mfma_f32_16x16x32_bf16 v[60:63], v[152:155], v[192:195], v[60:63]
	v_mfma_f32_16x16x32_bf16 v[56:59], v[168:171], v[192:195], v[56:59]
	v_mfma_f32_16x16x32_bf16 v[44:47], v[152:155], v[200:203], v[44:47]
	v_mfma_f32_16x16x32_bf16 v[40:43], v[168:171], v[200:203], v[40:43]
	v_mfma_f32_16x16x32_bf16 v[28:31], v[152:155], v[208:211], v[28:31]
	v_mfma_f32_16x16x32_bf16 v[24:27], v[168:171], v[208:211], v[24:27]
	v_mfma_f32_16x16x32_bf16 v[12:15], v[152:155], v[216:219], v[12:15]
	v_mfma_f32_16x16x32_bf16 v[8:11], v[168:171], v[216:219], v[8:11]
	s_setprio 0
	s_setprio 1
	v_mfma_f32_16x16x32_bf16 v[52:55], v[172:175], v[188:191], v[52:55]
	v_mfma_f32_16x16x32_bf16 v[48:51], v[180:183], v[188:191], v[48:51]
	v_mfma_f32_16x16x32_bf16 v[36:39], v[172:175], v[196:199], v[36:39]
	v_mfma_f32_16x16x32_bf16 v[32:35], v[180:183], v[196:199], v[32:35]
	v_mfma_f32_16x16x32_bf16 v[20:23], v[172:175], v[204:207], v[20:23]
	v_mfma_f32_16x16x32_bf16 v[16:19], v[180:183], v[204:207], v[16:19]
	v_mfma_f32_16x16x32_bf16 v[4:7], v[172:175], v[212:215], v[4:7]
	v_mfma_f32_16x16x32_bf16 v[0:3], v[180:183], v[212:215], v[0:3]
	v_mfma_f32_16x16x32_bf16 v[52:55], v[176:179], v[192:195], v[52:55]
	v_mfma_f32_16x16x32_bf16 v[48:51], v[184:187], v[192:195], v[48:51]
	v_mfma_f32_16x16x32_bf16 v[36:39], v[176:179], v[200:203], v[36:39]
	v_mfma_f32_16x16x32_bf16 v[32:35], v[184:187], v[200:203], v[32:35]
	v_mfma_f32_16x16x32_bf16 v[20:23], v[176:179], v[208:211], v[20:23]
	v_mfma_f32_16x16x32_bf16 v[16:19], v[184:187], v[208:211], v[16:19]
	v_mfma_f32_16x16x32_bf16 v[4:7], v[176:179], v[216:219], v[4:7]
	v_mfma_f32_16x16x32_bf16 v[0:3], v[184:187], v[216:219], v[0:3]
	s_setprio 0
	s_add_i32 s40, s40, 2
	s_add_u32 s31, s31, 0x100
	s_addc_u32 s33, s33, 0
	s_add_u32 s10, s10, 0x100
	s_addc_u32 s11, s11, 0
	s_cmp_gt_u32 s40, 13
	s_barrier
	s_cbranch_scc0 .LBB0_635
	s_and_b64 vcc, exec, s[26:27]
	s_cbranch_vccz .LBB0_638
	s_barrier

.LBB0_723:
	ds_read_b128 v[150:153], v158
	ds_read_b128 v[162:165], v158 offset:1024
	ds_read_b128 v[166:169], v158 offset:2048
	ds_read_b128 v[170:173], v158 offset:3072
	ds_read_b128 v[174:177], v159
	ds_read_b128 v[178:181], v159 offset:1024
	ds_read_b128 v[182:185], v159 offset:2048
	ds_read_b128 v[186:189], v159 offset:3072
	s_add_u32 s10, s8, 0xfffc0080
	s_addc_u32 s11, s9, -1
	s_cmp_eq_u32 s43, 12
	s_cselect_b32 s13, s14, s11
	s_cselect_b32 s12, s15, s10
	s_cselect_b32 s11, s16, s19
	s_cselect_b32 s10, s17, s18
	v_lshl_add_u64 v[154:155], s[8:9], 0, v[140:141]
	s_add_i32 m0, s56, 0xc000
	ds_read_b128 v[190:193], v160
	ds_read_b128 v[194:197], v160 offset:1024
	ds_read_b128 v[198:201], v160 offset:2048
	ds_read_b128 v[202:205], v160 offset:3072
	ds_read_b128 v[206:209], v160 offset:4096
	ds_read_b128 v[210:213], v160 offset:5120
	ds_read_b128 v[214:217], v160 offset:6144
	ds_read_b128 v[218:221], v160 offset:7168
	global_load_lds_dwordx4 v[154:155], off
	v_lshl_add_u64 v[154:155], s[8:9], 0, v[138:139]
	s_add_i32 m0, s56, 0xe000
	s_nop 0
	global_load_lds_dwordx4 v[154:155], off
	s_waitcnt vmcnt(8)
	s_waitcnt lgkmcnt(0)
	s_barrier
	s_setprio 1
	s_waitcnt lgkmcnt(0)
	v_mfma_f32_16x16x32_bf16 v[124:127], v[150:153], v[190:193], v[124:127]
	v_mfma_f32_16x16x32_bf16 v[120:123], v[166:169], v[190:193], v[120:123]
	v_mfma_f32_16x16x32_bf16 v[116:119], v[150:153], v[198:201], v[116:119]
	v_mfma_f32_16x16x32_bf16 v[112:115], v[166:169], v[198:201], v[112:115]
	v_mfma_f32_16x16x32_bf16 v[108:111], v[150:153], v[206:209], v[108:111]
	v_mfma_f32_16x16x32_bf16 v[104:107], v[166:169], v[206:209], v[104:107]
	v_mfma_f32_16x16x32_bf16 v[100:103], v[150:153], v[214:217], v[100:103]
	v_mfma_f32_16x16x32_bf16 v[96:99], v[166:169], v[214:217], v[96:99]
	v_mfma_f32_16x16x32_bf16 v[124:127], v[162:165], v[194:197], v[124:127]
	v_mfma_f32_16x16x32_bf16 v[120:123], v[170:173], v[194:197], v[120:123]
	v_mfma_f32_16x16x32_bf16 v[116:119], v[162:165], v[202:205], v[116:119]
	v_mfma_f32_16x16x32_bf16 v[112:115], v[170:173], v[202:205], v[112:115]
	v_mfma_f32_16x16x32_bf16 v[108:111], v[162:165], v[210:213], v[108:111]
	v_mfma_f32_16x16x32_bf16 v[104:107], v[170:173], v[210:213], v[104:107]
	v_mfma_f32_16x16x32_bf16 v[100:103], v[162:165], v[218:221], v[100:103]
	v_mfma_f32_16x16x32_bf16 v[96:99], v[170:173], v[218:221], v[96:99]
	s_setprio 0
	s_setprio 1
	v_mfma_f32_16x16x32_bf16 v[60:63], v[174:177], v[190:193], v[60:63]
	v_mfma_f32_16x16x32_bf16 v[56:59], v[182:185], v[190:193], v[56:59]
	v_mfma_f32_16x16x32_bf16 v[52:55], v[174:177], v[198:201], v[52:55]
	v_mfma_f32_16x16x32_bf16 v[48:51], v[182:185], v[198:201], v[48:51]
	v_mfma_f32_16x16x32_bf16 v[44:47], v[174:177], v[206:209], v[44:47]
	v_mfma_f32_16x16x32_bf16 v[40:43], v[182:185], v[206:209], v[40:43]
	v_mfma_f32_16x16x32_bf16 v[36:39], v[174:177], v[214:217], v[36:39]
	v_mfma_f32_16x16x32_bf16 v[32:35], v[182:185], v[214:217], v[32:35]
	v_mfma_f32_16x16x32_bf16 v[60:63], v[178:181], v[194:197], v[60:63]
	v_mfma_f32_16x16x32_bf16 v[56:59], v[186:189], v[194:197], v[56:59]
	v_mfma_f32_16x16x32_bf16 v[52:55], v[178:181], v[202:205], v[52:55]
	v_mfma_f32_16x16x32_bf16 v[48:51], v[186:189], v[202:205], v[48:51]
	v_mfma_f32_16x16x32_bf16 v[44:47], v[178:181], v[210:213], v[44:47]
	v_mfma_f32_16x16x32_bf16 v[40:43], v[186:189], v[210:213], v[40:43]
	v_mfma_f32_16x16x32_bf16 v[36:39], v[178:181], v[218:221], v[36:39]
	v_mfma_f32_16x16x32_bf16 v[32:35], v[186:189], v[218:221], v[32:35]
	s_setprio 0
	s_barrier
	s_add_i32 s45, s67, s41
	v_lshl_add_u64 v[154:155], s[10:11], 0, v[130:131]
	s_mov_b32 m0, s45
	ds_read_b128 v[190:193], v160 offset:16384
	ds_read_b128 v[194:197], v160 offset:17408
	ds_read_b128 v[198:201], v160 offset:18432
	ds_read_b128 v[202:205], v160 offset:19456
	ds_read_b128 v[206:209], v160 offset:20480
	ds_read_b128 v[210:213], v160 offset:21504
	ds_read_b128 v[214:217], v160 offset:22528
	ds_read_b128 v[218:221], v160 offset:23552
	global_load_lds_dwordx4 v[154:155], off
	s_add_i32 m0, s45, 0x2000
	s_add_u32 s54, s10, 0x40000
	v_lshl_add_u64 v[222:223], s[10:11], 0, v[134:135]
	s_addc_u32 s55, s11, 0
	s_add_i32 s45, s68, s41
	global_load_lds_dwordx4 v[222:223], off
	v_lshl_add_u64 v[224:225], s[54:55], 0, v[130:131]
	s_mov_b32 m0, s45
	v_lshl_add_u64 v[226:227], s[12:13], 0, v[132:133]
	global_load_lds_dwordx4 v[224:225], off
	v_lshl_add_u64 v[224:225], s[54:55], 0, v[134:135]
	s_add_i32 m0, s45, 0x2000
	s_nop 0
	global_load_lds_dwordx4 v[224:225], off
	v_lshl_add_u64 v[224:225], s[12:13], 0, v[128:129]
	s_mov_b32 m0, s56
	s_nop 0
	global_load_lds_dwordx4 v[224:225], off
	s_mov_b32 m0, s57
	s_nop 0
	global_load_lds_dwordx4 v[226:227], off
	s_waitcnt vmcnt(8)
	s_waitcnt lgkmcnt(0)
	s_barrier
	s_setprio 1
	s_waitcnt lgkmcnt(0)
	v_mfma_f32_16x16x32_bf16 v[92:95], v[150:153], v[190:193], v[92:95]
	v_mfma_f32_16x16x32_bf16 v[88:91], v[166:169], v[190:193], v[88:91]
	v_mfma_f32_16x16x32_bf16 v[84:87], v[150:153], v[198:201], v[84:87]
	v_mfma_f32_16x16x32_bf16 v[80:83], v[166:169], v[198:201], v[80:83]
	v_mfma_f32_16x16x32_bf16 v[76:79], v[150:153], v[206:209], v[76:79]
	v_mfma_f32_16x16x32_bf16 v[72:75], v[166:169], v[206:209], v[72:75]
	v_mfma_f32_16x16x32_bf16 v[68:71], v[150:153], v[214:217], v[68:71]
	v_mfma_f32_16x16x32_bf16 v[64:67], v[166:169], v[214:217], v[64:67]
	v_mfma_f32_16x16x32_bf16 v[92:95], v[162:165], v[194:197], v[92:95]
	v_mfma_f32_16x16x32_bf16 v[88:91], v[170:173], v[194:197], v[88:91]
	v_mfma_f32_16x16x32_bf16 v[84:87], v[162:165], v[202:205], v[84:87]
	v_mfma_f32_16x16x32_bf16 v[80:83], v[170:173], v[202:205], v[80:83]
	v_mfma_f32_16x16x32_bf16 v[76:79], v[162:165], v[210:213], v[76:79]
	v_mfma_f32_16x16x32_bf16 v[72:75], v[170:173], v[210:213], v[72:75]
	v_mfma_f32_16x16x32_bf16 v[68:71], v[162:165], v[218:221], v[68:71]
	v_mfma_f32_16x16x32_bf16 v[64:67], v[170:173], v[218:221], v[64:67]
	s_setprio 0
	s_setprio 1
	v_mfma_f32_16x16x32_bf16 v[28:31], v[174:177], v[190:193], v[28:31]
	v_mfma_f32_16x16x32_bf16 v[24:27], v[182:185], v[190:193], v[24:27]
	v_mfma_f32_16x16x32_bf16 v[20:23], v[174:177], v[198:201], v[20:23]
	v_mfma_f32_16x16x32_bf16 v[16:19], v[182:185], v[198:201], v[16:19]
	v_mfma_f32_16x16x32_bf16 v[12:15], v[174:177], v[206:209], v[12:15]
	v_mfma_f32_16x16x32_bf16 v[8:11], v[182:185], v[206:209], v[8:11]
	v_mfma_f32_16x16x32_bf16 v[4:7], v[174:177], v[214:217], v[4:7]
	v_mfma_f32_16x16x32_bf16 v[0:3], v[182:185], v[214:217], v[0:3]
	v_mfma_f32_16x16x32_bf16 v[28:31], v[178:181], v[194:197], v[28:31]
	v_mfma_f32_16x16x32_bf16 v[24:27], v[186:189], v[194:197], v[24:27]
	v_mfma_f32_16x16x32_bf16 v[20:23], v[178:181], v[202:205], v[20:23]
	v_mfma_f32_16x16x32_bf16 v[16:19], v[186:189], v[202:205], v[16:19]
	v_mfma_f32_16x16x32_bf16 v[12:15], v[178:181], v[210:213], v[12:15]
	v_mfma_f32_16x16x32_bf16 v[8:11], v[186:189], v[210:213], v[8:11]
	v_mfma_f32_16x16x32_bf16 v[4:7], v[178:181], v[218:221], v[4:7]
	v_mfma_f32_16x16x32_bf16 v[0:3], v[186:189], v[218:221], v[0:3]
	s_setprio 0
	s_barrier
	s_add_i32 s45, 0, 0x18000
	v_add_u32_e32 v147, s45, v157
	s_add_i32 s54, 0, 0x1c000
	ds_read_b128 v[150:153], v147
	ds_read_b128 v[162:165], v147 offset:1024
	ds_read_b128 v[166:169], v147 offset:2048
	ds_read_b128 v[170:173], v147 offset:3072
	v_add_u32_e32 v147, s54, v157
	ds_read_b128 v[174:177], v147
	ds_read_b128 v[178:181], v147 offset:1024
	ds_read_b128 v[182:185], v147 offset:2048
	ds_read_b128 v[186:189], v147 offset:3072
	s_add_u32 s12, s12, 0x40000
	s_addc_u32 s13, s13, 0
	s_mov_b32 m0, s58
	v_lshl_add_u64 v[228:229], s[12:13], 0, v[128:129]
	ds_read_b128 v[190:193], v160 offset:32768
	ds_read_b128 v[194:197], v160 offset:33792
	ds_read_b128 v[198:201], v160 offset:34816
	ds_read_b128 v[202:205], v160 offset:35840
	ds_read_b128 v[206:209], v160 offset:36864
	ds_read_b128 v[210:213], v160 offset:37888
	ds_read_b128 v[214:217], v160 offset:38912
	ds_read_b128 v[218:221], v160 offset:39936
	global_load_lds_dwordx4 v[228:229], off
	v_lshl_add_u64 v[228:229], s[12:13], 0, v[132:133]
	s_mov_b32 m0, s59
	s_nop 0
	global_load_lds_dwordx4 v[228:229], off
	s_waitcnt vmcnt(8)
	s_waitcnt lgkmcnt(0)
	s_barrier
	s_setprio 1
	s_waitcnt lgkmcnt(0)
	v_mfma_f32_16x16x32_bf16 v[124:127], v[150:153], v[190:193], v[124:127]
	v_mfma_f32_16x16x32_bf16 v[120:123], v[166:169], v[190:193], v[120:123]
	v_mfma_f32_16x16x32_bf16 v[116:119], v[150:153], v[198:201], v[116:119]
	v_mfma_f32_16x16x32_bf16 v[112:115], v[166:169], v[198:201], v[112:115]
	v_mfma_f32_16x16x32_bf16 v[108:111], v[150:153], v[206:209], v[108:111]
	v_mfma_f32_16x16x32_bf16 v[104:107], v[166:169], v[206:209], v[104:107]
	v_mfma_f32_16x16x32_bf16 v[100:103], v[150:153], v[214:217], v[100:103]
	v_mfma_f32_16x16x32_bf16 v[96:99], v[166:169], v[214:217], v[96:99]
	v_mfma_f32_16x16x32_bf16 v[124:127], v[162:165], v[194:197], v[124:127]
	v_mfma_f32_16x16x32_bf16 v[120:123], v[170:173], v[194:197], v[120:123]
	v_mfma_f32_16x16x32_bf16 v[116:119], v[162:165], v[202:205], v[116:119]
	v_mfma_f32_16x16x32_bf16 v[112:115], v[170:173], v[202:205], v[112:115]
	v_mfma_f32_16x16x32_bf16 v[108:111], v[162:165], v[210:213], v[108:111]
	v_mfma_f32_16x16x32_bf16 v[104:107], v[170:173], v[210:213], v[104:107]
	v_mfma_f32_16x16x32_bf16 v[100:103], v[162:165], v[218:221], v[100:103]
	v_mfma_f32_16x16x32_bf16 v[96:99], v[170:173], v[218:221], v[96:99]
	s_setprio 0
	s_setprio 1
	v_mfma_f32_16x16x32_bf16 v[60:63], v[174:177], v[190:193], v[60:63]
	v_mfma_f32_16x16x32_bf16 v[56:59], v[182:185], v[190:193], v[56:59]
	v_mfma_f32_16x16x32_bf16 v[52:55], v[174:177], v[198:201], v[52:55]
	v_mfma_f32_16x16x32_bf16 v[48:51], v[182:185], v[198:201], v[48:51]
	v_mfma_f32_16x16x32_bf16 v[44:47], v[174:177], v[206:209], v[44:47]
	v_mfma_f32_16x16x32_bf16 v[40:43], v[182:185], v[206:209], v[40:43]
	v_mfma_f32_16x16x32_bf16 v[36:39], v[174:177], v[214:217], v[36:39]
	v_mfma_f32_16x16x32_bf16 v[32:35], v[182:185], v[214:217], v[32:35]
	v_mfma_f32_16x16x32_bf16 v[60:63], v[178:181], v[194:197], v[60:63]
	v_mfma_f32_16x16x32_bf16 v[56:59], v[186:189], v[194:197], v[56:59]
	v_mfma_f32_16x16x32_bf16 v[52:55], v[178:181], v[202:205], v[52:55]
	v_mfma_f32_16x16x32_bf16 v[48:51], v[186:189], v[202:205], v[48:51]
	v_mfma_f32_16x16x32_bf16 v[44:47], v[178:181], v[210:213], v[44:47]
	v_mfma_f32_16x16x32_bf16 v[40:43], v[186:189], v[210:213], v[40:43]
	v_mfma_f32_16x16x32_bf16 v[36:39], v[178:181], v[218:221], v[36:39]
	v_mfma_f32_16x16x32_bf16 v[32:35], v[186:189], v[218:221], v[32:35]
	s_setprio 0
	s_barrier
	s_add_i32 s12, s45, s41
	v_lshl_add_u64 v[154:155], v[154:155], 0, s[26:27]
	s_mov_b32 m0, s12
	ds_read_b128 v[190:193], v160 offset:49152
	ds_read_b128 v[194:197], v160 offset:50176
	ds_read_b128 v[198:201], v160 offset:51200
	ds_read_b128 v[202:205], v160 offset:52224
	ds_read_b128 v[206:209], v160 offset:53248
	ds_read_b128 v[210:213], v160 offset:54272
	ds_read_b128 v[214:217], v160 offset:55296
	ds_read_b128 v[218:221], v160 offset:56320
	global_load_lds_dwordx4 v[154:155], off
	s_add_i32 m0, s12, 0x2000
	s_add_u32 s10, s10, 0x40080
	v_lshl_add_u64 v[154:155], v[222:223], 0, s[26:27]
	s_addc_u32 s11, s11, 0
	s_add_i32 s12, s54, s41
	global_load_lds_dwordx4 v[154:155], off
	v_lshl_add_u64 v[154:155], s[10:11], 0, v[130:131]
	s_mov_b32 m0, s12
	s_nop 0
	global_load_lds_dwordx4 v[154:155], off
	v_lshl_add_u64 v[154:155], s[10:11], 0, v[134:135]
	s_add_i32 m0, s12, 0x2000
	s_nop 0
	global_load_lds_dwordx4 v[154:155], off
	v_lshl_add_u64 v[154:155], v[224:225], 0, s[26:27]
	s_mov_b32 m0, s63
	s_nop 0
	global_load_lds_dwordx4 v[154:155], off
	v_lshl_add_u64 v[154:155], v[226:227], 0, s[26:27]
	s_mov_b32 m0, s64
	s_nop 0
	global_load_lds_dwordx4 v[154:155], off
	s_waitcnt vmcnt(8)
	s_waitcnt lgkmcnt(0)
	s_barrier
	s_setprio 1
	s_waitcnt lgkmcnt(0)
	v_mfma_f32_16x16x32_bf16 v[92:95], v[150:153], v[190:193], v[92:95]
	v_mfma_f32_16x16x32_bf16 v[88:91], v[166:169], v[190:193], v[88:91]
	v_mfma_f32_16x16x32_bf16 v[84:87], v[150:153], v[198:201], v[84:87]
	v_mfma_f32_16x16x32_bf16 v[80:83], v[166:169], v[198:201], v[80:83]
	v_mfma_f32_16x16x32_bf16 v[76:79], v[150:153], v[206:209], v[76:79]
	v_mfma_f32_16x16x32_bf16 v[72:75], v[166:169], v[206:209], v[72:75]
	v_mfma_f32_16x16x32_bf16 v[68:71], v[150:153], v[214:217], v[68:71]
	v_mfma_f32_16x16x32_bf16 v[64:67], v[166:169], v[214:217], v[64:67]
	v_mfma_f32_16x16x32_bf16 v[92:95], v[162:165], v[194:197], v[92:95]
	v_mfma_f32_16x16x32_bf16 v[88:91], v[170:173], v[194:197], v[88:91]
	v_mfma_f32_16x16x32_bf16 v[84:87], v[162:165], v[202:205], v[84:87]
	v_mfma_f32_16x16x32_bf16 v[80:83], v[170:173], v[202:205], v[80:83]
	v_mfma_f32_16x16x32_bf16 v[76:79], v[162:165], v[210:213], v[76:79]
	v_mfma_f32_16x16x32_bf16 v[72:75], v[170:173], v[210:213], v[72:75]
	v_mfma_f32_16x16x32_bf16 v[68:71], v[162:165], v[218:221], v[68:71]
	v_mfma_f32_16x16x32_bf16 v[64:67], v[170:173], v[218:221], v[64:67]
	s_setprio 0
	s_setprio 1
	v_mfma_f32_16x16x32_bf16 v[28:31], v[174:177], v[190:193], v[28:31]
	v_mfma_f32_16x16x32_bf16 v[24:27], v[182:185], v[190:193], v[24:27]
	v_mfma_f32_16x16x32_bf16 v[20:23], v[174:177], v[198:201], v[20:23]
	v_mfma_f32_16x16x32_bf16 v[16:19], v[182:185], v[198:201], v[16:19]
	v_mfma_f32_16x16x32_bf16 v[12:15], v[174:177], v[206:209], v[12:15]
	v_mfma_f32_16x16x32_bf16 v[8:11], v[182:185], v[206:209], v[8:11]
	v_mfma_f32_16x16x32_bf16 v[4:7], v[174:177], v[214:217], v[4:7]
	v_mfma_f32_16x16x32_bf16 v[0:3], v[182:185], v[214:217], v[0:3]
	v_mfma_f32_16x16x32_bf16 v[28:31], v[178:181], v[194:197], v[28:31]
	v_mfma_f32_16x16x32_bf16 v[24:27], v[186:189], v[194:197], v[24:27]
	v_mfma_f32_16x16x32_bf16 v[20:23], v[178:181], v[202:205], v[20:23]
	v_mfma_f32_16x16x32_bf16 v[16:19], v[186:189], v[202:205], v[16:19]
	v_mfma_f32_16x16x32_bf16 v[12:15], v[178:181], v[210:213], v[12:15]
	v_mfma_f32_16x16x32_bf16 v[8:11], v[186:189], v[210:213], v[8:11]
	v_mfma_f32_16x16x32_bf16 v[4:7], v[178:181], v[218:221], v[4:7]
	v_mfma_f32_16x16x32_bf16 v[0:3], v[186:189], v[218:221], v[0:3]
	s_setprio 0
	s_add_i32 s43, s43, 2
	s_add_u32 s18, s18, 0x100
	s_addc_u32 s19, s19, 0
	s_add_u32 s8, s8, 0x100
	s_addc_u32 s9, s9, 0
	s_cmp_gt_u32 s43, 13
	s_barrier
	s_cbranch_scc0 .LBB0_723
	s_and_b64 vcc, exec, s[28:29]
	s_cbranch_vccz .LBB0_726
	s_barrier

.LBB0_980:
	ds_read_b128 v[144:147], v151
	ds_read_b128 v[156:159], v151 offset:1024
	ds_read_b128 v[160:163], v151 offset:2048
	ds_read_b128 v[164:167], v151 offset:3072
	ds_read_b128 v[168:171], v152
	ds_read_b128 v[172:175], v152 offset:1024
	ds_read_b128 v[176:179], v152 offset:2048
	ds_read_b128 v[180:183], v152 offset:3072
	s_add_u32 s38, s36, 0xfffc0080
	s_addc_u32 s39, s37, -1
	s_cmp_eq_u32 s62, 12
	s_cselect_b32 s41, s23, s39
	s_cselect_b32 s40, s29, s38
	s_cselect_b32 s39, s21, s61
	s_cselect_b32 s38, s59, s60
	v_lshl_add_u64 v[216:217], s[36:37], 0, v[136:137]
	s_add_i32 m0, s31, 0xc000
	ds_read_b128 v[184:187], v153
	ds_read_b128 v[188:191], v153 offset:1024
	ds_read_b128 v[192:195], v153 offset:2048
	ds_read_b128 v[196:199], v153 offset:3072
	ds_read_b128 v[200:203], v153 offset:4096
	ds_read_b128 v[204:207], v153 offset:5120
	ds_read_b128 v[208:211], v153 offset:6144
	ds_read_b128 v[212:215], v153 offset:7168
	global_load_lds_dwordx4 v[216:217], off
	v_lshl_add_u64 v[216:217], s[36:37], 0, v[138:139]
	s_add_i32 m0, s31, 0xe000
	s_nop 0
	global_load_lds_dwordx4 v[216:217], off
	s_waitcnt vmcnt(8)
	s_waitcnt lgkmcnt(0)
	s_barrier
	s_setprio 1
	s_waitcnt lgkmcnt(0)
	v_mfma_f32_16x16x32_bf16 v[124:127], v[144:147], v[184:187], v[124:127]
	v_mfma_f32_16x16x32_bf16 v[120:123], v[160:163], v[184:187], v[120:123]
	v_mfma_f32_16x16x32_bf16 v[108:111], v[144:147], v[192:195], v[108:111]
	v_mfma_f32_16x16x32_bf16 v[104:107], v[160:163], v[192:195], v[104:107]
	v_mfma_f32_16x16x32_bf16 v[92:95], v[144:147], v[200:203], v[92:95]
	v_mfma_f32_16x16x32_bf16 v[88:91], v[160:163], v[200:203], v[88:91]
	v_mfma_f32_16x16x32_bf16 v[76:79], v[144:147], v[208:211], v[76:79]
	v_mfma_f32_16x16x32_bf16 v[72:75], v[160:163], v[208:211], v[72:75]
	v_mfma_f32_16x16x32_bf16 v[124:127], v[156:159], v[188:191], v[124:127]
	v_mfma_f32_16x16x32_bf16 v[120:123], v[164:167], v[188:191], v[120:123]
	v_mfma_f32_16x16x32_bf16 v[108:111], v[156:159], v[196:199], v[108:111]
	v_mfma_f32_16x16x32_bf16 v[104:107], v[164:167], v[196:199], v[104:107]
	v_mfma_f32_16x16x32_bf16 v[92:95], v[156:159], v[204:207], v[92:95]
	v_mfma_f32_16x16x32_bf16 v[88:91], v[164:167], v[204:207], v[88:91]
	v_mfma_f32_16x16x32_bf16 v[76:79], v[156:159], v[212:215], v[76:79]
	v_mfma_f32_16x16x32_bf16 v[72:75], v[164:167], v[212:215], v[72:75]
	s_setprio 0
	s_setprio 1
	v_mfma_f32_16x16x32_bf16 v[116:119], v[168:171], v[184:187], v[116:119]
	v_mfma_f32_16x16x32_bf16 v[112:115], v[176:179], v[184:187], v[112:115]
	v_mfma_f32_16x16x32_bf16 v[100:103], v[168:171], v[192:195], v[100:103]
	v_mfma_f32_16x16x32_bf16 v[96:99], v[176:179], v[192:195], v[96:99]
	v_mfma_f32_16x16x32_bf16 v[84:87], v[168:171], v[200:203], v[84:87]
	v_mfma_f32_16x16x32_bf16 v[80:83], v[176:179], v[200:203], v[80:83]
	v_mfma_f32_16x16x32_bf16 v[68:71], v[168:171], v[208:211], v[68:71]
	v_mfma_f32_16x16x32_bf16 v[64:67], v[176:179], v[208:211], v[64:67]
	v_mfma_f32_16x16x32_bf16 v[116:119], v[172:175], v[188:191], v[116:119]
	v_mfma_f32_16x16x32_bf16 v[112:115], v[180:183], v[188:191], v[112:115]
	v_mfma_f32_16x16x32_bf16 v[100:103], v[172:175], v[196:199], v[100:103]
	v_mfma_f32_16x16x32_bf16 v[96:99], v[180:183], v[196:199], v[96:99]
	v_mfma_f32_16x16x32_bf16 v[84:87], v[172:175], v[204:207], v[84:87]
	v_mfma_f32_16x16x32_bf16 v[80:83], v[180:183], v[204:207], v[80:83]
	v_mfma_f32_16x16x32_bf16 v[68:71], v[172:175], v[212:215], v[68:71]
	v_mfma_f32_16x16x32_bf16 v[64:67], v[180:183], v[212:215], v[64:67]
	s_setprio 0
	s_barrier
	s_add_i32 s63, s57, s44
	v_lshl_add_u64 v[216:217], s[38:39], 0, v[130:131]
	s_mov_b32 m0, s63
	ds_read_b128 v[184:187], v153 offset:16384
	ds_read_b128 v[188:191], v153 offset:17408
	ds_read_b128 v[192:195], v153 offset:18432
	ds_read_b128 v[196:199], v153 offset:19456
	ds_read_b128 v[200:203], v153 offset:20480
	ds_read_b128 v[204:207], v153 offset:21504
	ds_read_b128 v[208:211], v153 offset:22528
	ds_read_b128 v[212:215], v153 offset:23552
	global_load_lds_dwordx4 v[216:217], off
	s_add_i32 m0, s63, 0x2000
	s_add_u32 s64, s38, 0x40000
	v_lshl_add_u64 v[218:219], s[38:39], 0, v[134:135]
	s_addc_u32 s65, s39, 0
	s_add_i32 s63, s58, s44
	global_load_lds_dwordx4 v[218:219], off
	v_lshl_add_u64 v[220:221], s[64:65], 0, v[130:131]
	s_mov_b32 m0, s63
	v_lshl_add_u64 v[222:223], s[40:41], 0, v[132:133]
	global_load_lds_dwordx4 v[220:221], off
	v_lshl_add_u64 v[220:221], s[64:65], 0, v[134:135]
	s_add_i32 m0, s63, 0x2000
	s_nop 0
	global_load_lds_dwordx4 v[220:221], off
	v_lshl_add_u64 v[220:221], s[40:41], 0, v[128:129]
	s_mov_b32 m0, s31
	s_nop 0
	global_load_lds_dwordx4 v[220:221], off
	s_mov_b32 m0, s45
	s_nop 0
	global_load_lds_dwordx4 v[222:223], off
	s_waitcnt vmcnt(8)
	s_waitcnt lgkmcnt(0)
	s_barrier
	s_setprio 1
	s_waitcnt lgkmcnt(0)
	v_mfma_f32_16x16x32_bf16 v[60:63], v[144:147], v[184:187], v[60:63]
	v_mfma_f32_16x16x32_bf16 v[56:59], v[160:163], v[184:187], v[56:59]
	v_mfma_f32_16x16x32_bf16 v[44:47], v[144:147], v[192:195], v[44:47]
	v_mfma_f32_16x16x32_bf16 v[40:43], v[160:163], v[192:195], v[40:43]
	v_mfma_f32_16x16x32_bf16 v[28:31], v[144:147], v[200:203], v[28:31]
	v_mfma_f32_16x16x32_bf16 v[24:27], v[160:163], v[200:203], v[24:27]
	v_mfma_f32_16x16x32_bf16 v[12:15], v[144:147], v[208:211], v[12:15]
	v_mfma_f32_16x16x32_bf16 v[8:11], v[160:163], v[208:211], v[8:11]
	v_mfma_f32_16x16x32_bf16 v[60:63], v[156:159], v[188:191], v[60:63]
	v_mfma_f32_16x16x32_bf16 v[56:59], v[164:167], v[188:191], v[56:59]
	v_mfma_f32_16x16x32_bf16 v[44:47], v[156:159], v[196:199], v[44:47]
	v_mfma_f32_16x16x32_bf16 v[40:43], v[164:167], v[196:199], v[40:43]
	v_mfma_f32_16x16x32_bf16 v[28:31], v[156:159], v[204:207], v[28:31]
	v_mfma_f32_16x16x32_bf16 v[24:27], v[164:167], v[204:207], v[24:27]
	v_mfma_f32_16x16x32_bf16 v[12:15], v[156:159], v[212:215], v[12:15]
	v_mfma_f32_16x16x32_bf16 v[8:11], v[164:167], v[212:215], v[8:11]
	s_setprio 0
	s_setprio 1
	v_mfma_f32_16x16x32_bf16 v[52:55], v[168:171], v[184:187], v[52:55]
	v_mfma_f32_16x16x32_bf16 v[48:51], v[176:179], v[184:187], v[48:51]
	v_mfma_f32_16x16x32_bf16 v[36:39], v[168:171], v[192:195], v[36:39]
	v_mfma_f32_16x16x32_bf16 v[32:35], v[176:179], v[192:195], v[32:35]
	v_mfma_f32_16x16x32_bf16 v[20:23], v[168:171], v[200:203], v[20:23]
	v_mfma_f32_16x16x32_bf16 v[16:19], v[176:179], v[200:203], v[16:19]
	v_mfma_f32_16x16x32_bf16 v[4:7], v[168:171], v[208:211], v[4:7]
	v_mfma_f32_16x16x32_bf16 v[0:3], v[176:179], v[208:211], v[0:3]
	v_mfma_f32_16x16x32_bf16 v[52:55], v[172:175], v[188:191], v[52:55]
	v_mfma_f32_16x16x32_bf16 v[48:51], v[180:183], v[188:191], v[48:51]
	v_mfma_f32_16x16x32_bf16 v[36:39], v[172:175], v[196:199], v[36:39]
	v_mfma_f32_16x16x32_bf16 v[32:35], v[180:183], v[196:199], v[32:35]
	v_mfma_f32_16x16x32_bf16 v[20:23], v[172:175], v[204:207], v[20:23]
	v_mfma_f32_16x16x32_bf16 v[16:19], v[180:183], v[204:207], v[16:19]
	v_mfma_f32_16x16x32_bf16 v[4:7], v[172:175], v[212:215], v[4:7]
	v_mfma_f32_16x16x32_bf16 v[0:3], v[180:183], v[212:215], v[0:3]
	s_setprio 0
	s_barrier
	s_add_i32 s63, 0, 0x18000
	v_add_u32_e32 v155, s63, v149
	s_add_i32 s64, 0, 0x1c000
	ds_read_b128 v[144:147], v155
	ds_read_b128 v[156:159], v155 offset:1024
	ds_read_b128 v[160:163], v155 offset:2048
	ds_read_b128 v[164:167], v155 offset:3072
	v_add_u32_e32 v155, s64, v149
	ds_read_b128 v[168:171], v155
	ds_read_b128 v[172:175], v155 offset:1024
	ds_read_b128 v[176:179], v155 offset:2048
	ds_read_b128 v[180:183], v155 offset:3072
	s_add_u32 s40, s40, 0x40000
	s_addc_u32 s41, s41, 0
	s_mov_b32 m0, s46
	v_lshl_add_u64 v[224:225], s[40:41], 0, v[128:129]
	ds_read_b128 v[184:187], v153 offset:32768
	ds_read_b128 v[188:191], v153 offset:33792
	ds_read_b128 v[192:195], v153 offset:34816
	ds_read_b128 v[196:199], v153 offset:35840
	ds_read_b128 v[200:203], v153 offset:36864
	ds_read_b128 v[204:207], v153 offset:37888
	ds_read_b128 v[208:211], v153 offset:38912
	ds_read_b128 v[212:215], v153 offset:39936
	global_load_lds_dwordx4 v[224:225], off
	v_lshl_add_u64 v[224:225], s[40:41], 0, v[132:133]
	s_mov_b32 m0, s47
	s_nop 0
	global_load_lds_dwordx4 v[224:225], off
	s_waitcnt vmcnt(8)
	s_waitcnt lgkmcnt(0)
	s_barrier
	s_setprio 1
	s_waitcnt lgkmcnt(0)
	v_mfma_f32_16x16x32_bf16 v[124:127], v[144:147], v[184:187], v[124:127]
	v_mfma_f32_16x16x32_bf16 v[120:123], v[160:163], v[184:187], v[120:123]
	v_mfma_f32_16x16x32_bf16 v[108:111], v[144:147], v[192:195], v[108:111]
	v_mfma_f32_16x16x32_bf16 v[104:107], v[160:163], v[192:195], v[104:107]
	v_mfma_f32_16x16x32_bf16 v[92:95], v[144:147], v[200:203], v[92:95]
	v_mfma_f32_16x16x32_bf16 v[88:91], v[160:163], v[200:203], v[88:91]
	v_mfma_f32_16x16x32_bf16 v[76:79], v[144:147], v[208:211], v[76:79]
	v_mfma_f32_16x16x32_bf16 v[72:75], v[160:163], v[208:211], v[72:75]
	v_mfma_f32_16x16x32_bf16 v[124:127], v[156:159], v[188:191], v[124:127]
	v_mfma_f32_16x16x32_bf16 v[120:123], v[164:167], v[188:191], v[120:123]
	v_mfma_f32_16x16x32_bf16 v[108:111], v[156:159], v[196:199], v[108:111]
	v_mfma_f32_16x16x32_bf16 v[104:107], v[164:167], v[196:199], v[104:107]
	v_mfma_f32_16x16x32_bf16 v[92:95], v[156:159], v[204:207], v[92:95]
	v_mfma_f32_16x16x32_bf16 v[88:91], v[164:167], v[204:207], v[88:91]
	v_mfma_f32_16x16x32_bf16 v[76:79], v[156:159], v[212:215], v[76:79]
	v_mfma_f32_16x16x32_bf16 v[72:75], v[164:167], v[212:215], v[72:75]
	s_setprio 0
	s_setprio 1
	v_mfma_f32_16x16x32_bf16 v[116:119], v[168:171], v[184:187], v[116:119]
	v_mfma_f32_16x16x32_bf16 v[112:115], v[176:179], v[184:187], v[112:115]
	v_mfma_f32_16x16x32_bf16 v[100:103], v[168:171], v[192:195], v[100:103]
	v_mfma_f32_16x16x32_bf16 v[96:99], v[176:179], v[192:195], v[96:99]
	v_mfma_f32_16x16x32_bf16 v[84:87], v[168:171], v[200:203], v[84:87]
	v_mfma_f32_16x16x32_bf16 v[80:83], v[176:179], v[200:203], v[80:83]
	v_mfma_f32_16x16x32_bf16 v[68:71], v[168:171], v[208:211], v[68:71]
	v_mfma_f32_16x16x32_bf16 v[64:67], v[176:179], v[208:211], v[64:67]
	v_mfma_f32_16x16x32_bf16 v[116:119], v[172:175], v[188:191], v[116:119]
	v_mfma_f32_16x16x32_bf16 v[112:115], v[180:183], v[188:191], v[112:115]
	v_mfma_f32_16x16x32_bf16 v[100:103], v[172:175], v[196:199], v[100:103]
	v_mfma_f32_16x16x32_bf16 v[96:99], v[180:183], v[196:199], v[96:99]
	v_mfma_f32_16x16x32_bf16 v[84:87], v[172:175], v[204:207], v[84:87]
	v_mfma_f32_16x16x32_bf16 v[80:83], v[180:183], v[204:207], v[80:83]
	v_mfma_f32_16x16x32_bf16 v[68:71], v[172:175], v[212:215], v[68:71]
	v_mfma_f32_16x16x32_bf16 v[64:67], v[180:183], v[212:215], v[64:67]
	s_setprio 0
	s_barrier
	s_add_i32 s40, s63, s44
	v_lshl_add_u64 v[216:217], v[216:217], 0, s[16:17]
	s_mov_b32 m0, s40
	ds_read_b128 v[184:187], v153 offset:49152
	ds_read_b128 v[188:191], v153 offset:50176
	ds_read_b128 v[192:195], v153 offset:51200
	ds_read_b128 v[196:199], v153 offset:52224
	ds_read_b128 v[200:203], v153 offset:53248
	ds_read_b128 v[204:207], v153 offset:54272
	ds_read_b128 v[208:211], v153 offset:55296
	ds_read_b128 v[212:215], v153 offset:56320
	global_load_lds_dwordx4 v[216:217], off
	s_add_i32 m0, s40, 0x2000
	s_add_u32 s38, s38, 0x40080
	v_lshl_add_u64 v[216:217], v[218:219], 0, s[16:17]
	s_addc_u32 s39, s39, 0
	s_add_i32 s40, s64, s44
	global_load_lds_dwordx4 v[216:217], off
	v_lshl_add_u64 v[216:217], s[38:39], 0, v[130:131]
	s_mov_b32 m0, s40
	s_nop 0
	global_load_lds_dwordx4 v[216:217], off
	v_lshl_add_u64 v[216:217], s[38:39], 0, v[134:135]
	s_add_i32 m0, s40, 0x2000
	s_nop 0
	global_load_lds_dwordx4 v[216:217], off
	v_lshl_add_u64 v[216:217], v[220:221], 0, s[16:17]
	s_mov_b32 m0, s53
	s_nop 0
	global_load_lds_dwordx4 v[216:217], off
	v_lshl_add_u64 v[216:217], v[222:223], 0, s[16:17]
	s_mov_b32 m0, s54
	s_nop 0
	global_load_lds_dwordx4 v[216:217], off
	s_waitcnt vmcnt(8)
	s_waitcnt lgkmcnt(0)
	s_barrier
	s_setprio 1
	s_waitcnt lgkmcnt(0)
	v_mfma_f32_16x16x32_bf16 v[60:63], v[144:147], v[184:187], v[60:63]
	v_mfma_f32_16x16x32_bf16 v[56:59], v[160:163], v[184:187], v[56:59]
	v_mfma_f32_16x16x32_bf16 v[44:47], v[144:147], v[192:195], v[44:47]
	v_mfma_f32_16x16x32_bf16 v[40:43], v[160:163], v[192:195], v[40:43]
	v_mfma_f32_16x16x32_bf16 v[28:31], v[144:147], v[200:203], v[28:31]
	v_mfma_f32_16x16x32_bf16 v[24:27], v[160:163], v[200:203], v[24:27]
	v_mfma_f32_16x16x32_bf16 v[12:15], v[144:147], v[208:211], v[12:15]
	v_mfma_f32_16x16x32_bf16 v[8:11], v[160:163], v[208:211], v[8:11]
	v_mfma_f32_16x16x32_bf16 v[60:63], v[156:159], v[188:191], v[60:63]
	v_mfma_f32_16x16x32_bf16 v[56:59], v[164:167], v[188:191], v[56:59]
	v_mfma_f32_16x16x32_bf16 v[44:47], v[156:159], v[196:199], v[44:47]
	v_mfma_f32_16x16x32_bf16 v[40:43], v[164:167], v[196:199], v[40:43]
	v_mfma_f32_16x16x32_bf16 v[28:31], v[156:159], v[204:207], v[28:31]
	v_mfma_f32_16x16x32_bf16 v[24:27], v[164:167], v[204:207], v[24:27]
	v_mfma_f32_16x16x32_bf16 v[12:15], v[156:159], v[212:215], v[12:15]
	v_mfma_f32_16x16x32_bf16 v[8:11], v[164:167], v[212:215], v[8:11]
	s_setprio 0
	s_setprio 1
	v_mfma_f32_16x16x32_bf16 v[52:55], v[168:171], v[184:187], v[52:55]
	v_mfma_f32_16x16x32_bf16 v[48:51], v[176:179], v[184:187], v[48:51]
	v_mfma_f32_16x16x32_bf16 v[36:39], v[168:171], v[192:195], v[36:39]
	v_mfma_f32_16x16x32_bf16 v[32:35], v[176:179], v[192:195], v[32:35]
	v_mfma_f32_16x16x32_bf16 v[20:23], v[168:171], v[200:203], v[20:23]
	v_mfma_f32_16x16x32_bf16 v[16:19], v[176:179], v[200:203], v[16:19]
	v_mfma_f32_16x16x32_bf16 v[4:7], v[168:171], v[208:211], v[4:7]
	v_mfma_f32_16x16x32_bf16 v[0:3], v[176:179], v[208:211], v[0:3]
	v_mfma_f32_16x16x32_bf16 v[52:55], v[172:175], v[188:191], v[52:55]
	v_mfma_f32_16x16x32_bf16 v[48:51], v[180:183], v[188:191], v[48:51]
	v_mfma_f32_16x16x32_bf16 v[36:39], v[172:175], v[196:199], v[36:39]
	v_mfma_f32_16x16x32_bf16 v[32:35], v[180:183], v[196:199], v[32:35]
	v_mfma_f32_16x16x32_bf16 v[20:23], v[172:175], v[204:207], v[20:23]
	v_mfma_f32_16x16x32_bf16 v[16:19], v[180:183], v[204:207], v[16:19]
	v_mfma_f32_16x16x32_bf16 v[4:7], v[172:175], v[212:215], v[4:7]
	v_mfma_f32_16x16x32_bf16 v[0:3], v[180:183], v[212:215], v[0:3]
	s_setprio 0
	s_add_i32 s62, s62, 2
	s_add_u32 s60, s60, 0x100
	s_addc_u32 s61, s61, 0
	s_add_u32 s36, s36, 0x100
	s_addc_u32 s37, s37, 0
	s_cmp_gt_u32 s62, 13
	s_barrier
	s_cbranch_scc0 .LBB0_980
	s_and_b64 vcc, exec, s[18:19]
	s_cbranch_vccz .LBB0_983
	s_barrier

.LBB0_1072:
	ds_read_b128 v[144:147], v151
	ds_read_b128 v[156:159], v151 offset:1024
	ds_read_b128 v[160:163], v151 offset:2048
	ds_read_b128 v[164:167], v151 offset:3072
	ds_read_b128 v[168:171], v152
	ds_read_b128 v[172:175], v152 offset:1024
	ds_read_b128 v[176:179], v152 offset:2048
	ds_read_b128 v[180:183], v152 offset:3072
	s_add_u32 s36, s30, 0xfffc0080
	s_addc_u32 s37, s31, -1
	s_cmp_eq_u32 s63, 12
	s_cselect_b32 s39, s21, s37
	s_cselect_b32 s38, s59, s36
	s_cselect_b32 s37, s19, s62
	s_cselect_b32 s36, s60, s61
	v_lshl_add_u64 v[216:217], s[30:31], 0, v[138:139]
	s_add_i32 m0, s27, 0xc000
	ds_read_b128 v[184:187], v153
	ds_read_b128 v[188:191], v153 offset:1024
	ds_read_b128 v[192:195], v153 offset:2048
	ds_read_b128 v[196:199], v153 offset:3072
	ds_read_b128 v[200:203], v153 offset:4096
	ds_read_b128 v[204:207], v153 offset:5120
	ds_read_b128 v[208:211], v153 offset:6144
	ds_read_b128 v[212:215], v153 offset:7168
	global_load_lds_dwordx4 v[216:217], off
	v_lshl_add_u64 v[216:217], s[30:31], 0, v[136:137]
	s_add_i32 m0, s27, 0xe000
	s_nop 0
	global_load_lds_dwordx4 v[216:217], off
	s_waitcnt vmcnt(8)
	s_waitcnt lgkmcnt(0)
	s_barrier
	s_setprio 1
	s_waitcnt lgkmcnt(0)
	v_mfma_f32_16x16x32_bf16 v[124:127], v[144:147], v[184:187], v[124:127]
	v_mfma_f32_16x16x32_bf16 v[120:123], v[160:163], v[184:187], v[120:123]
	v_mfma_f32_16x16x32_bf16 v[108:111], v[144:147], v[192:195], v[108:111]
	v_mfma_f32_16x16x32_bf16 v[104:107], v[160:163], v[192:195], v[104:107]
	v_mfma_f32_16x16x32_bf16 v[92:95], v[144:147], v[200:203], v[92:95]
	v_mfma_f32_16x16x32_bf16 v[88:91], v[160:163], v[200:203], v[88:91]
	v_mfma_f32_16x16x32_bf16 v[76:79], v[144:147], v[208:211], v[76:79]
	v_mfma_f32_16x16x32_bf16 v[72:75], v[160:163], v[208:211], v[72:75]
	v_mfma_f32_16x16x32_bf16 v[124:127], v[156:159], v[188:191], v[124:127]
	v_mfma_f32_16x16x32_bf16 v[120:123], v[164:167], v[188:191], v[120:123]
	v_mfma_f32_16x16x32_bf16 v[108:111], v[156:159], v[196:199], v[108:111]
	v_mfma_f32_16x16x32_bf16 v[104:107], v[164:167], v[196:199], v[104:107]
	v_mfma_f32_16x16x32_bf16 v[92:95], v[156:159], v[204:207], v[92:95]
	v_mfma_f32_16x16x32_bf16 v[88:91], v[164:167], v[204:207], v[88:91]
	v_mfma_f32_16x16x32_bf16 v[76:79], v[156:159], v[212:215], v[76:79]
	v_mfma_f32_16x16x32_bf16 v[72:75], v[164:167], v[212:215], v[72:75]
	s_setprio 0
	s_setprio 1
	v_mfma_f32_16x16x32_bf16 v[116:119], v[168:171], v[184:187], v[116:119]
	v_mfma_f32_16x16x32_bf16 v[112:115], v[176:179], v[184:187], v[112:115]
	v_mfma_f32_16x16x32_bf16 v[100:103], v[168:171], v[192:195], v[100:103]
	v_mfma_f32_16x16x32_bf16 v[96:99], v[176:179], v[192:195], v[96:99]
	v_mfma_f32_16x16x32_bf16 v[84:87], v[168:171], v[200:203], v[84:87]
	v_mfma_f32_16x16x32_bf16 v[80:83], v[176:179], v[200:203], v[80:83]
	v_mfma_f32_16x16x32_bf16 v[68:71], v[168:171], v[208:211], v[68:71]
	v_mfma_f32_16x16x32_bf16 v[64:67], v[176:179], v[208:211], v[64:67]
	v_mfma_f32_16x16x32_bf16 v[116:119], v[172:175], v[188:191], v[116:119]
	v_mfma_f32_16x16x32_bf16 v[112:115], v[180:183], v[188:191], v[112:115]
	v_mfma_f32_16x16x32_bf16 v[100:103], v[172:175], v[196:199], v[100:103]
	v_mfma_f32_16x16x32_bf16 v[96:99], v[180:183], v[196:199], v[96:99]
	v_mfma_f32_16x16x32_bf16 v[84:87], v[172:175], v[204:207], v[84:87]
	v_mfma_f32_16x16x32_bf16 v[80:83], v[180:183], v[204:207], v[80:83]
	v_mfma_f32_16x16x32_bf16 v[68:71], v[172:175], v[212:215], v[68:71]
	v_mfma_f32_16x16x32_bf16 v[64:67], v[180:183], v[212:215], v[64:67]
	s_setprio 0
	s_barrier
	s_add_i32 s64, s55, s42
	v_lshl_add_u64 v[216:217], s[36:37], 0, v[130:131]
	s_mov_b32 m0, s64
	ds_read_b128 v[184:187], v153 offset:16384
	ds_read_b128 v[188:191], v153 offset:17408
	ds_read_b128 v[192:195], v153 offset:18432
	ds_read_b128 v[196:199], v153 offset:19456
	ds_read_b128 v[200:203], v153 offset:20480
	ds_read_b128 v[204:207], v153 offset:21504
	ds_read_b128 v[208:211], v153 offset:22528
	ds_read_b128 v[212:215], v153 offset:23552
	global_load_lds_dwordx4 v[216:217], off
	s_add_i32 m0, s64, 0x2000
	s_add_u32 s64, s36, 0x40000
	v_lshl_add_u64 v[218:219], s[36:37], 0, v[134:135]
	s_addc_u32 s65, s37, 0
	s_add_i32 s66, s56, s42
	global_load_lds_dwordx4 v[218:219], off
	v_lshl_add_u64 v[220:221], s[64:65], 0, v[130:131]
	s_mov_b32 m0, s66
	v_lshl_add_u64 v[222:223], s[38:39], 0, v[132:133]
	global_load_lds_dwordx4 v[220:221], off
	v_lshl_add_u64 v[220:221], s[64:65], 0, v[134:135]
	s_add_i32 m0, s66, 0x2000
	s_nop 0
	global_load_lds_dwordx4 v[220:221], off
	v_lshl_add_u64 v[220:221], s[38:39], 0, v[128:129]
	s_mov_b32 m0, s27
	s_nop 0
	global_load_lds_dwordx4 v[220:221], off
	s_mov_b32 m0, s43
	s_nop 0
	global_load_lds_dwordx4 v[222:223], off
	s_waitcnt vmcnt(8)
	s_waitcnt lgkmcnt(0)
	s_barrier
	s_setprio 1
	s_waitcnt lgkmcnt(0)
	v_mfma_f32_16x16x32_bf16 v[60:63], v[144:147], v[184:187], v[60:63]
	v_mfma_f32_16x16x32_bf16 v[56:59], v[160:163], v[184:187], v[56:59]
	v_mfma_f32_16x16x32_bf16 v[44:47], v[144:147], v[192:195], v[44:47]
	v_mfma_f32_16x16x32_bf16 v[40:43], v[160:163], v[192:195], v[40:43]
	v_mfma_f32_16x16x32_bf16 v[28:31], v[144:147], v[200:203], v[28:31]
	v_mfma_f32_16x16x32_bf16 v[24:27], v[160:163], v[200:203], v[24:27]
	v_mfma_f32_16x16x32_bf16 v[12:15], v[144:147], v[208:211], v[12:15]
	v_mfma_f32_16x16x32_bf16 v[8:11], v[160:163], v[208:211], v[8:11]
	v_mfma_f32_16x16x32_bf16 v[60:63], v[156:159], v[188:191], v[60:63]
	v_mfma_f32_16x16x32_bf16 v[56:59], v[164:167], v[188:191], v[56:59]
	v_mfma_f32_16x16x32_bf16 v[44:47], v[156:159], v[196:199], v[44:47]
	v_mfma_f32_16x16x32_bf16 v[40:43], v[164:167], v[196:199], v[40:43]
	v_mfma_f32_16x16x32_bf16 v[28:31], v[156:159], v[204:207], v[28:31]
	v_mfma_f32_16x16x32_bf16 v[24:27], v[164:167], v[204:207], v[24:27]
	v_mfma_f32_16x16x32_bf16 v[12:15], v[156:159], v[212:215], v[12:15]
	v_mfma_f32_16x16x32_bf16 v[8:11], v[164:167], v[212:215], v[8:11]
	s_setprio 0
	s_setprio 1
	v_mfma_f32_16x16x32_bf16 v[52:55], v[168:171], v[184:187], v[52:55]
	v_mfma_f32_16x16x32_bf16 v[48:51], v[176:179], v[184:187], v[48:51]
	v_mfma_f32_16x16x32_bf16 v[36:39], v[168:171], v[192:195], v[36:39]
	v_mfma_f32_16x16x32_bf16 v[32:35], v[176:179], v[192:195], v[32:35]
	v_mfma_f32_16x16x32_bf16 v[20:23], v[168:171], v[200:203], v[20:23]
	v_mfma_f32_16x16x32_bf16 v[16:19], v[176:179], v[200:203], v[16:19]
	v_mfma_f32_16x16x32_bf16 v[4:7], v[168:171], v[208:211], v[4:7]
	v_mfma_f32_16x16x32_bf16 v[0:3], v[176:179], v[208:211], v[0:3]
	v_mfma_f32_16x16x32_bf16 v[52:55], v[172:175], v[188:191], v[52:55]
	v_mfma_f32_16x16x32_bf16 v[48:51], v[180:183], v[188:191], v[48:51]
	v_mfma_f32_16x16x32_bf16 v[36:39], v[172:175], v[196:199], v[36:39]
	v_mfma_f32_16x16x32_bf16 v[32:35], v[180:183], v[196:199], v[32:35]
	v_mfma_f32_16x16x32_bf16 v[20:23], v[172:175], v[204:207], v[20:23]
	v_mfma_f32_16x16x32_bf16 v[16:19], v[180:183], v[204:207], v[16:19]
	v_mfma_f32_16x16x32_bf16 v[4:7], v[172:175], v[212:215], v[4:7]
	v_mfma_f32_16x16x32_bf16 v[0:3], v[180:183], v[212:215], v[0:3]
	s_setprio 0
	s_barrier
	s_add_i32 s64, 0, 0x18000
	v_add_u32_e32 v155, s64, v149
	s_add_i32 s65, 0, 0x1c000
	ds_read_b128 v[144:147], v155
	ds_read_b128 v[156:159], v155 offset:1024
	ds_read_b128 v[160:163], v155 offset:2048
	ds_read_b128 v[164:167], v155 offset:3072
	v_add_u32_e32 v155, s65, v149
	ds_read_b128 v[168:171], v155
	ds_read_b128 v[172:175], v155 offset:1024
	ds_read_b128 v[176:179], v155 offset:2048
	ds_read_b128 v[180:183], v155 offset:3072
	s_add_u32 s38, s38, 0x40000
	s_addc_u32 s39, s39, 0
	s_mov_b32 m0, s44
	v_lshl_add_u64 v[224:225], s[38:39], 0, v[128:129]
	ds_read_b128 v[184:187], v153 offset:32768
	ds_read_b128 v[188:191], v153 offset:33792
	ds_read_b128 v[192:195], v153 offset:34816
	ds_read_b128 v[196:199], v153 offset:35840
	ds_read_b128 v[200:203], v153 offset:36864
	ds_read_b128 v[204:207], v153 offset:37888
	ds_read_b128 v[208:211], v153 offset:38912
	ds_read_b128 v[212:215], v153 offset:39936
	global_load_lds_dwordx4 v[224:225], off
	v_lshl_add_u64 v[224:225], s[38:39], 0, v[132:133]
	s_mov_b32 m0, s45
	s_nop 0
	global_load_lds_dwordx4 v[224:225], off
	s_waitcnt vmcnt(8)
	s_waitcnt lgkmcnt(0)
	s_barrier
	s_setprio 1
	s_waitcnt lgkmcnt(0)
	v_mfma_f32_16x16x32_bf16 v[124:127], v[144:147], v[184:187], v[124:127]
	v_mfma_f32_16x16x32_bf16 v[120:123], v[160:163], v[184:187], v[120:123]
	v_mfma_f32_16x16x32_bf16 v[108:111], v[144:147], v[192:195], v[108:111]
	v_mfma_f32_16x16x32_bf16 v[104:107], v[160:163], v[192:195], v[104:107]
	v_mfma_f32_16x16x32_bf16 v[92:95], v[144:147], v[200:203], v[92:95]
	v_mfma_f32_16x16x32_bf16 v[88:91], v[160:163], v[200:203], v[88:91]
	v_mfma_f32_16x16x32_bf16 v[76:79], v[144:147], v[208:211], v[76:79]
	v_mfma_f32_16x16x32_bf16 v[72:75], v[160:163], v[208:211], v[72:75]
	v_mfma_f32_16x16x32_bf16 v[124:127], v[156:159], v[188:191], v[124:127]
	v_mfma_f32_16x16x32_bf16 v[120:123], v[164:167], v[188:191], v[120:123]
	v_mfma_f32_16x16x32_bf16 v[108:111], v[156:159], v[196:199], v[108:111]
	v_mfma_f32_16x16x32_bf16 v[104:107], v[164:167], v[196:199], v[104:107]
	v_mfma_f32_16x16x32_bf16 v[92:95], v[156:159], v[204:207], v[92:95]
	v_mfma_f32_16x16x32_bf16 v[88:91], v[164:167], v[204:207], v[88:91]
	v_mfma_f32_16x16x32_bf16 v[76:79], v[156:159], v[212:215], v[76:79]
	v_mfma_f32_16x16x32_bf16 v[72:75], v[164:167], v[212:215], v[72:75]
	s_setprio 0
	s_setprio 1
	v_mfma_f32_16x16x32_bf16 v[116:119], v[168:171], v[184:187], v[116:119]
	v_mfma_f32_16x16x32_bf16 v[112:115], v[176:179], v[184:187], v[112:115]
	v_mfma_f32_16x16x32_bf16 v[100:103], v[168:171], v[192:195], v[100:103]
	v_mfma_f32_16x16x32_bf16 v[96:99], v[176:179], v[192:195], v[96:99]
	v_mfma_f32_16x16x32_bf16 v[84:87], v[168:171], v[200:203], v[84:87]
	v_mfma_f32_16x16x32_bf16 v[80:83], v[176:179], v[200:203], v[80:83]
	v_mfma_f32_16x16x32_bf16 v[68:71], v[168:171], v[208:211], v[68:71]
	v_mfma_f32_16x16x32_bf16 v[64:67], v[176:179], v[208:211], v[64:67]
	v_mfma_f32_16x16x32_bf16 v[116:119], v[172:175], v[188:191], v[116:119]
	v_mfma_f32_16x16x32_bf16 v[112:115], v[180:183], v[188:191], v[112:115]
	v_mfma_f32_16x16x32_bf16 v[100:103], v[172:175], v[196:199], v[100:103]
	v_mfma_f32_16x16x32_bf16 v[96:99], v[180:183], v[196:199], v[96:99]
	v_mfma_f32_16x16x32_bf16 v[84:87], v[172:175], v[204:207], v[84:87]
	v_mfma_f32_16x16x32_bf16 v[80:83], v[180:183], v[204:207], v[80:83]
	v_mfma_f32_16x16x32_bf16 v[68:71], v[172:175], v[212:215], v[68:71]
	v_mfma_f32_16x16x32_bf16 v[64:67], v[180:183], v[212:215], v[64:67]
	s_setprio 0
	s_barrier
	s_add_i32 s38, s64, s42
	v_lshl_add_u64 v[216:217], v[216:217], 0, s[14:15]
	s_mov_b32 m0, s38
	ds_read_b128 v[184:187], v153 offset:49152
	ds_read_b128 v[188:191], v153 offset:50176
	ds_read_b128 v[192:195], v153 offset:51200
	ds_read_b128 v[196:199], v153 offset:52224
	ds_read_b128 v[200:203], v153 offset:53248
	ds_read_b128 v[204:207], v153 offset:54272
	ds_read_b128 v[208:211], v153 offset:55296
	ds_read_b128 v[212:215], v153 offset:56320
	global_load_lds_dwordx4 v[216:217], off
	s_add_i32 m0, s38, 0x2000
	s_add_u32 s36, s36, 0x40080
	v_lshl_add_u64 v[216:217], v[218:219], 0, s[14:15]
	s_addc_u32 s37, s37, 0
	s_add_i32 s38, s65, s42
	global_load_lds_dwordx4 v[216:217], off
	v_lshl_add_u64 v[216:217], s[36:37], 0, v[130:131]
	s_mov_b32 m0, s38
	s_nop 0
	global_load_lds_dwordx4 v[216:217], off
	v_lshl_add_u64 v[216:217], s[36:37], 0, v[134:135]
	s_add_i32 m0, s38, 0x2000
	s_nop 0
	global_load_lds_dwordx4 v[216:217], off
	v_lshl_add_u64 v[216:217], v[220:221], 0, s[14:15]
	s_mov_b32 m0, s47
	s_nop 0
	global_load_lds_dwordx4 v[216:217], off
	v_lshl_add_u64 v[216:217], v[222:223], 0, s[14:15]
	s_mov_b32 m0, s52
	s_nop 0
	global_load_lds_dwordx4 v[216:217], off
	s_waitcnt vmcnt(8)
	s_waitcnt lgkmcnt(0)
	s_barrier
	s_setprio 1
	s_waitcnt lgkmcnt(0)
	v_mfma_f32_16x16x32_bf16 v[60:63], v[144:147], v[184:187], v[60:63]
	v_mfma_f32_16x16x32_bf16 v[56:59], v[160:163], v[184:187], v[56:59]
	v_mfma_f32_16x16x32_bf16 v[44:47], v[144:147], v[192:195], v[44:47]
	v_mfma_f32_16x16x32_bf16 v[40:43], v[160:163], v[192:195], v[40:43]
	v_mfma_f32_16x16x32_bf16 v[28:31], v[144:147], v[200:203], v[28:31]
	v_mfma_f32_16x16x32_bf16 v[24:27], v[160:163], v[200:203], v[24:27]
	v_mfma_f32_16x16x32_bf16 v[12:15], v[144:147], v[208:211], v[12:15]
	v_mfma_f32_16x16x32_bf16 v[8:11], v[160:163], v[208:211], v[8:11]
	v_mfma_f32_16x16x32_bf16 v[60:63], v[156:159], v[188:191], v[60:63]
	v_mfma_f32_16x16x32_bf16 v[56:59], v[164:167], v[188:191], v[56:59]
	v_mfma_f32_16x16x32_bf16 v[44:47], v[156:159], v[196:199], v[44:47]
	v_mfma_f32_16x16x32_bf16 v[40:43], v[164:167], v[196:199], v[40:43]
	v_mfma_f32_16x16x32_bf16 v[28:31], v[156:159], v[204:207], v[28:31]
	v_mfma_f32_16x16x32_bf16 v[24:27], v[164:167], v[204:207], v[24:27]
	v_mfma_f32_16x16x32_bf16 v[12:15], v[156:159], v[212:215], v[12:15]
	v_mfma_f32_16x16x32_bf16 v[8:11], v[164:167], v[212:215], v[8:11]
	s_setprio 0
	s_setprio 1
	v_mfma_f32_16x16x32_bf16 v[52:55], v[168:171], v[184:187], v[52:55]
	v_mfma_f32_16x16x32_bf16 v[48:51], v[176:179], v[184:187], v[48:51]
	v_mfma_f32_16x16x32_bf16 v[36:39], v[168:171], v[192:195], v[36:39]
	v_mfma_f32_16x16x32_bf16 v[32:35], v[176:179], v[192:195], v[32:35]
	v_mfma_f32_16x16x32_bf16 v[20:23], v[168:171], v[200:203], v[20:23]
	v_mfma_f32_16x16x32_bf16 v[16:19], v[176:179], v[200:203], v[16:19]
	v_mfma_f32_16x16x32_bf16 v[4:7], v[168:171], v[208:211], v[4:7]
	v_mfma_f32_16x16x32_bf16 v[0:3], v[176:179], v[208:211], v[0:3]
	v_mfma_f32_16x16x32_bf16 v[52:55], v[172:175], v[188:191], v[52:55]
	v_mfma_f32_16x16x32_bf16 v[48:51], v[180:183], v[188:191], v[48:51]
	v_mfma_f32_16x16x32_bf16 v[36:39], v[172:175], v[196:199], v[36:39]
	v_mfma_f32_16x16x32_bf16 v[32:35], v[180:183], v[196:199], v[32:35]
	v_mfma_f32_16x16x32_bf16 v[20:23], v[172:175], v[204:207], v[20:23]
	v_mfma_f32_16x16x32_bf16 v[16:19], v[180:183], v[204:207], v[16:19]
	v_mfma_f32_16x16x32_bf16 v[4:7], v[172:175], v[212:215], v[4:7]
	v_mfma_f32_16x16x32_bf16 v[0:3], v[180:183], v[212:215], v[0:3]
	s_setprio 0
	s_add_i32 s63, s63, 2
	s_add_u32 s61, s61, 0x100
	s_addc_u32 s62, s62, 0
	s_add_u32 s30, s30, 0x100
	s_addc_u32 s31, s31, 0
	s_cmp_gt_u32 s63, 13
	s_barrier
	s_cbranch_scc0 .LBB0_1072
	s_and_b64 vcc, exec, s[16:17]
	s_cbranch_vccz .LBB0_1075
	s_barrier

.LBB0_1150:
	ds_read_b128 v[144:147], v151
	ds_read_b128 v[156:159], v151 offset:1024
	ds_read_b128 v[160:163], v151 offset:2048
	ds_read_b128 v[164:167], v151 offset:3072
	ds_read_b128 v[168:171], v152
	ds_read_b128 v[172:175], v152 offset:1024
	ds_read_b128 v[176:179], v152 offset:2048
	ds_read_b128 v[180:183], v152 offset:3072
	s_add_u32 s42, s40, 0xfff00080
	s_addc_u32 s43, s41, -1
	s_cmp_eq_u32 s64, 60
	s_cselect_b32 s45, s25, s43
	s_cselect_b32 s44, s37, s42
	s_cselect_b32 s43, s23, s63
	s_cselect_b32 s42, s61, s62
	v_lshl_add_u64 v[216:217], s[40:41], 0, v[136:137]
	s_add_i32 m0, s39, 0xc000
	ds_read_b128 v[184:187], v153
	ds_read_b128 v[188:191], v153 offset:1024
	ds_read_b128 v[192:195], v153 offset:2048
	ds_read_b128 v[196:199], v153 offset:3072
	ds_read_b128 v[200:203], v153 offset:4096
	ds_read_b128 v[204:207], v153 offset:5120
	ds_read_b128 v[208:211], v153 offset:6144
	ds_read_b128 v[212:215], v153 offset:7168
	global_load_lds_dwordx4 v[216:217], off
	v_lshl_add_u64 v[216:217], s[40:41], 0, v[138:139]
	s_add_i32 m0, s39, 0xe000
	s_nop 0
	global_load_lds_dwordx4 v[216:217], off
	s_waitcnt vmcnt(8)
	s_waitcnt lgkmcnt(0)
	s_barrier
	s_setprio 1
	s_waitcnt lgkmcnt(0)
	v_mfma_f32_16x16x32_bf16 v[124:127], v[144:147], v[184:187], v[124:127]
	v_mfma_f32_16x16x32_bf16 v[120:123], v[160:163], v[184:187], v[120:123]
	v_mfma_f32_16x16x32_bf16 v[108:111], v[144:147], v[192:195], v[108:111]
	v_mfma_f32_16x16x32_bf16 v[104:107], v[160:163], v[192:195], v[104:107]
	v_mfma_f32_16x16x32_bf16 v[92:95], v[144:147], v[200:203], v[92:95]
	v_mfma_f32_16x16x32_bf16 v[88:91], v[160:163], v[200:203], v[88:91]
	v_mfma_f32_16x16x32_bf16 v[76:79], v[144:147], v[208:211], v[76:79]
	v_mfma_f32_16x16x32_bf16 v[72:75], v[160:163], v[208:211], v[72:75]
	v_mfma_f32_16x16x32_bf16 v[124:127], v[156:159], v[188:191], v[124:127]
	v_mfma_f32_16x16x32_bf16 v[120:123], v[164:167], v[188:191], v[120:123]
	v_mfma_f32_16x16x32_bf16 v[108:111], v[156:159], v[196:199], v[108:111]
	v_mfma_f32_16x16x32_bf16 v[104:107], v[164:167], v[196:199], v[104:107]
	v_mfma_f32_16x16x32_bf16 v[92:95], v[156:159], v[204:207], v[92:95]
	v_mfma_f32_16x16x32_bf16 v[88:91], v[164:167], v[204:207], v[88:91]
	v_mfma_f32_16x16x32_bf16 v[76:79], v[156:159], v[212:215], v[76:79]
	v_mfma_f32_16x16x32_bf16 v[72:75], v[164:167], v[212:215], v[72:75]
	s_setprio 0
	s_setprio 1
	v_mfma_f32_16x16x32_bf16 v[116:119], v[168:171], v[184:187], v[116:119]
	v_mfma_f32_16x16x32_bf16 v[112:115], v[176:179], v[184:187], v[112:115]
	v_mfma_f32_16x16x32_bf16 v[100:103], v[168:171], v[192:195], v[100:103]
	v_mfma_f32_16x16x32_bf16 v[96:99], v[176:179], v[192:195], v[96:99]
	v_mfma_f32_16x16x32_bf16 v[84:87], v[168:171], v[200:203], v[84:87]
	v_mfma_f32_16x16x32_bf16 v[80:83], v[176:179], v[200:203], v[80:83]
	v_mfma_f32_16x16x32_bf16 v[68:71], v[168:171], v[208:211], v[68:71]
	v_mfma_f32_16x16x32_bf16 v[64:67], v[176:179], v[208:211], v[64:67]
	v_mfma_f32_16x16x32_bf16 v[116:119], v[172:175], v[188:191], v[116:119]
	v_mfma_f32_16x16x32_bf16 v[112:115], v[180:183], v[188:191], v[112:115]
	v_mfma_f32_16x16x32_bf16 v[100:103], v[172:175], v[196:199], v[100:103]
	v_mfma_f32_16x16x32_bf16 v[96:99], v[180:183], v[196:199], v[96:99]
	v_mfma_f32_16x16x32_bf16 v[84:87], v[172:175], v[204:207], v[84:87]
	v_mfma_f32_16x16x32_bf16 v[80:83], v[180:183], v[204:207], v[80:83]
	v_mfma_f32_16x16x32_bf16 v[68:71], v[172:175], v[212:215], v[68:71]
	v_mfma_f32_16x16x32_bf16 v[64:67], v[180:183], v[212:215], v[64:67]
	s_setprio 0
	s_barrier
	s_add_i32 s65, s59, s46
	v_lshl_add_u64 v[216:217], s[42:43], 0, v[130:131]
	s_mov_b32 m0, s65
	ds_read_b128 v[184:187], v153 offset:16384
	ds_read_b128 v[188:191], v153 offset:17408
	ds_read_b128 v[192:195], v153 offset:18432
	ds_read_b128 v[196:199], v153 offset:19456
	ds_read_b128 v[200:203], v153 offset:20480
	ds_read_b128 v[204:207], v153 offset:21504
	ds_read_b128 v[208:211], v153 offset:22528
	ds_read_b128 v[212:215], v153 offset:23552
	global_load_lds_dwordx4 v[216:217], off
	s_add_i32 m0, s65, 0x2000
	s_add_u32 s66, s42, 0x100000
	v_lshl_add_u64 v[218:219], s[42:43], 0, v[134:135]
	s_addc_u32 s67, s43, 0
	s_add_i32 s65, s60, s46
	global_load_lds_dwordx4 v[218:219], off
	v_lshl_add_u64 v[220:221], s[66:67], 0, v[130:131]
	s_mov_b32 m0, s65
	v_lshl_add_u64 v[222:223], s[44:45], 0, v[132:133]
	global_load_lds_dwordx4 v[220:221], off
	v_lshl_add_u64 v[220:221], s[66:67], 0, v[134:135]
	s_add_i32 m0, s65, 0x2000
	s_nop 0
	global_load_lds_dwordx4 v[220:221], off
	v_lshl_add_u64 v[220:221], s[44:45], 0, v[128:129]
	s_mov_b32 m0, s39
	s_nop 0
	global_load_lds_dwordx4 v[220:221], off
	s_mov_b32 m0, s47
	s_nop 0
	global_load_lds_dwordx4 v[222:223], off
	s_waitcnt vmcnt(8)
	s_waitcnt lgkmcnt(0)
	s_barrier
	s_setprio 1
	s_waitcnt lgkmcnt(0)
	v_mfma_f32_16x16x32_bf16 v[60:63], v[144:147], v[184:187], v[60:63]
	v_mfma_f32_16x16x32_bf16 v[56:59], v[160:163], v[184:187], v[56:59]
	v_mfma_f32_16x16x32_bf16 v[44:47], v[144:147], v[192:195], v[44:47]
	v_mfma_f32_16x16x32_bf16 v[40:43], v[160:163], v[192:195], v[40:43]
	v_mfma_f32_16x16x32_bf16 v[28:31], v[144:147], v[200:203], v[28:31]
	v_mfma_f32_16x16x32_bf16 v[24:27], v[160:163], v[200:203], v[24:27]
	v_mfma_f32_16x16x32_bf16 v[12:15], v[144:147], v[208:211], v[12:15]
	v_mfma_f32_16x16x32_bf16 v[8:11], v[160:163], v[208:211], v[8:11]
	v_mfma_f32_16x16x32_bf16 v[60:63], v[156:159], v[188:191], v[60:63]
	v_mfma_f32_16x16x32_bf16 v[56:59], v[164:167], v[188:191], v[56:59]
	v_mfma_f32_16x16x32_bf16 v[44:47], v[156:159], v[196:199], v[44:47]
	v_mfma_f32_16x16x32_bf16 v[40:43], v[164:167], v[196:199], v[40:43]
	v_mfma_f32_16x16x32_bf16 v[28:31], v[156:159], v[204:207], v[28:31]
	v_mfma_f32_16x16x32_bf16 v[24:27], v[164:167], v[204:207], v[24:27]
	v_mfma_f32_16x16x32_bf16 v[12:15], v[156:159], v[212:215], v[12:15]
	v_mfma_f32_16x16x32_bf16 v[8:11], v[164:167], v[212:215], v[8:11]
	s_setprio 0
	s_setprio 1
	v_mfma_f32_16x16x32_bf16 v[52:55], v[168:171], v[184:187], v[52:55]
	v_mfma_f32_16x16x32_bf16 v[48:51], v[176:179], v[184:187], v[48:51]
	v_mfma_f32_16x16x32_bf16 v[36:39], v[168:171], v[192:195], v[36:39]
	v_mfma_f32_16x16x32_bf16 v[32:35], v[176:179], v[192:195], v[32:35]
	v_mfma_f32_16x16x32_bf16 v[20:23], v[168:171], v[200:203], v[20:23]
	v_mfma_f32_16x16x32_bf16 v[16:19], v[176:179], v[200:203], v[16:19]
	v_mfma_f32_16x16x32_bf16 v[4:7], v[168:171], v[208:211], v[4:7]
	v_mfma_f32_16x16x32_bf16 v[0:3], v[176:179], v[208:211], v[0:3]
	v_mfma_f32_16x16x32_bf16 v[52:55], v[172:175], v[188:191], v[52:55]
	v_mfma_f32_16x16x32_bf16 v[48:51], v[180:183], v[188:191], v[48:51]
	v_mfma_f32_16x16x32_bf16 v[36:39], v[172:175], v[196:199], v[36:39]
	v_mfma_f32_16x16x32_bf16 v[32:35], v[180:183], v[196:199], v[32:35]
	v_mfma_f32_16x16x32_bf16 v[20:23], v[172:175], v[204:207], v[20:23]
	v_mfma_f32_16x16x32_bf16 v[16:19], v[180:183], v[204:207], v[16:19]
	v_mfma_f32_16x16x32_bf16 v[4:7], v[172:175], v[212:215], v[4:7]
	v_mfma_f32_16x16x32_bf16 v[0:3], v[180:183], v[212:215], v[0:3]
	s_setprio 0
	s_barrier
	s_add_i32 s65, 0, 0x18000
	v_add_u32_e32 v155, s65, v149
	s_add_i32 s66, 0, 0x1c000
	ds_read_b128 v[144:147], v155
	ds_read_b128 v[156:159], v155 offset:1024
	ds_read_b128 v[160:163], v155 offset:2048
	ds_read_b128 v[164:167], v155 offset:3072
	v_add_u32_e32 v155, s66, v149
	ds_read_b128 v[168:171], v155
	ds_read_b128 v[172:175], v155 offset:1024
	ds_read_b128 v[176:179], v155 offset:2048
	ds_read_b128 v[180:183], v155 offset:3072
	s_add_u32 s44, s44, 0x100000
	s_addc_u32 s45, s45, 0
	s_mov_b32 m0, s52
	v_lshl_add_u64 v[224:225], s[44:45], 0, v[128:129]
	ds_read_b128 v[184:187], v153 offset:32768
	ds_read_b128 v[188:191], v153 offset:33792
	ds_read_b128 v[192:195], v153 offset:34816
	ds_read_b128 v[196:199], v153 offset:35840
	ds_read_b128 v[200:203], v153 offset:36864
	ds_read_b128 v[204:207], v153 offset:37888
	ds_read_b128 v[208:211], v153 offset:38912
	ds_read_b128 v[212:215], v153 offset:39936
	global_load_lds_dwordx4 v[224:225], off
	v_lshl_add_u64 v[224:225], s[44:45], 0, v[132:133]
	s_mov_b32 m0, s53
	s_nop 0
	global_load_lds_dwordx4 v[224:225], off
	s_waitcnt vmcnt(8)
	s_waitcnt lgkmcnt(0)
	s_barrier
	s_setprio 1
	s_waitcnt lgkmcnt(0)
	v_mfma_f32_16x16x32_bf16 v[124:127], v[144:147], v[184:187], v[124:127]
	v_mfma_f32_16x16x32_bf16 v[120:123], v[160:163], v[184:187], v[120:123]
	v_mfma_f32_16x16x32_bf16 v[108:111], v[144:147], v[192:195], v[108:111]
	v_mfma_f32_16x16x32_bf16 v[104:107], v[160:163], v[192:195], v[104:107]
	v_mfma_f32_16x16x32_bf16 v[92:95], v[144:147], v[200:203], v[92:95]
	v_mfma_f32_16x16x32_bf16 v[88:91], v[160:163], v[200:203], v[88:91]
	v_mfma_f32_16x16x32_bf16 v[76:79], v[144:147], v[208:211], v[76:79]
	v_mfma_f32_16x16x32_bf16 v[72:75], v[160:163], v[208:211], v[72:75]
	v_mfma_f32_16x16x32_bf16 v[124:127], v[156:159], v[188:191], v[124:127]
	v_mfma_f32_16x16x32_bf16 v[120:123], v[164:167], v[188:191], v[120:123]
	v_mfma_f32_16x16x32_bf16 v[108:111], v[156:159], v[196:199], v[108:111]
	v_mfma_f32_16x16x32_bf16 v[104:107], v[164:167], v[196:199], v[104:107]
	v_mfma_f32_16x16x32_bf16 v[92:95], v[156:159], v[204:207], v[92:95]
	v_mfma_f32_16x16x32_bf16 v[88:91], v[164:167], v[204:207], v[88:91]
	v_mfma_f32_16x16x32_bf16 v[76:79], v[156:159], v[212:215], v[76:79]
	v_mfma_f32_16x16x32_bf16 v[72:75], v[164:167], v[212:215], v[72:75]
	s_setprio 0
	s_setprio 1
	v_mfma_f32_16x16x32_bf16 v[116:119], v[168:171], v[184:187], v[116:119]
	v_mfma_f32_16x16x32_bf16 v[112:115], v[176:179], v[184:187], v[112:115]
	v_mfma_f32_16x16x32_bf16 v[100:103], v[168:171], v[192:195], v[100:103]
	v_mfma_f32_16x16x32_bf16 v[96:99], v[176:179], v[192:195], v[96:99]
	v_mfma_f32_16x16x32_bf16 v[84:87], v[168:171], v[200:203], v[84:87]
	v_mfma_f32_16x16x32_bf16 v[80:83], v[176:179], v[200:203], v[80:83]
	v_mfma_f32_16x16x32_bf16 v[68:71], v[168:171], v[208:211], v[68:71]
	v_mfma_f32_16x16x32_bf16 v[64:67], v[176:179], v[208:211], v[64:67]
	v_mfma_f32_16x16x32_bf16 v[116:119], v[172:175], v[188:191], v[116:119]
	v_mfma_f32_16x16x32_bf16 v[112:115], v[180:183], v[188:191], v[112:115]
	v_mfma_f32_16x16x32_bf16 v[100:103], v[172:175], v[196:199], v[100:103]
	v_mfma_f32_16x16x32_bf16 v[96:99], v[180:183], v[196:199], v[96:99]
	v_mfma_f32_16x16x32_bf16 v[84:87], v[172:175], v[204:207], v[84:87]
	v_mfma_f32_16x16x32_bf16 v[80:83], v[180:183], v[204:207], v[80:83]
	v_mfma_f32_16x16x32_bf16 v[68:71], v[172:175], v[212:215], v[68:71]
	v_mfma_f32_16x16x32_bf16 v[64:67], v[180:183], v[212:215], v[64:67]
	s_setprio 0
	s_barrier
	s_add_i32 s44, s65, s46
	v_lshl_add_u64 v[216:217], v[216:217], 0, s[18:19]
	s_mov_b32 m0, s44
	ds_read_b128 v[184:187], v153 offset:49152
	ds_read_b128 v[188:191], v153 offset:50176
	ds_read_b128 v[192:195], v153 offset:51200
	ds_read_b128 v[196:199], v153 offset:52224
	ds_read_b128 v[200:203], v153 offset:53248
	ds_read_b128 v[204:207], v153 offset:54272
	ds_read_b128 v[208:211], v153 offset:55296
	ds_read_b128 v[212:215], v153 offset:56320
	global_load_lds_dwordx4 v[216:217], off
	s_add_i32 m0, s44, 0x2000
	s_add_u32 s42, s42, 0x100080
	v_lshl_add_u64 v[216:217], v[218:219], 0, s[18:19]
	s_addc_u32 s43, s43, 0
	s_add_i32 s44, s66, s46
	global_load_lds_dwordx4 v[216:217], off
	v_lshl_add_u64 v[216:217], s[42:43], 0, v[130:131]
	s_mov_b32 m0, s44
	s_nop 0
	global_load_lds_dwordx4 v[216:217], off
	v_lshl_add_u64 v[216:217], s[42:43], 0, v[134:135]
	s_add_i32 m0, s44, 0x2000
	s_nop 0
	global_load_lds_dwordx4 v[216:217], off
	v_lshl_add_u64 v[216:217], v[220:221], 0, s[18:19]
	s_mov_b32 m0, s55
	s_nop 0
	global_load_lds_dwordx4 v[216:217], off
	v_lshl_add_u64 v[216:217], v[222:223], 0, s[18:19]
	s_mov_b32 m0, s56
	s_nop 0
	global_load_lds_dwordx4 v[216:217], off
	s_waitcnt vmcnt(8)
	s_waitcnt lgkmcnt(0)
	s_barrier
	s_setprio 1
	s_waitcnt lgkmcnt(0)
	v_mfma_f32_16x16x32_bf16 v[60:63], v[144:147], v[184:187], v[60:63]
	v_mfma_f32_16x16x32_bf16 v[56:59], v[160:163], v[184:187], v[56:59]
	v_mfma_f32_16x16x32_bf16 v[44:47], v[144:147], v[192:195], v[44:47]
	v_mfma_f32_16x16x32_bf16 v[40:43], v[160:163], v[192:195], v[40:43]
	v_mfma_f32_16x16x32_bf16 v[28:31], v[144:147], v[200:203], v[28:31]
	v_mfma_f32_16x16x32_bf16 v[24:27], v[160:163], v[200:203], v[24:27]
	v_mfma_f32_16x16x32_bf16 v[12:15], v[144:147], v[208:211], v[12:15]
	v_mfma_f32_16x16x32_bf16 v[8:11], v[160:163], v[208:211], v[8:11]
	v_mfma_f32_16x16x32_bf16 v[60:63], v[156:159], v[188:191], v[60:63]
	v_mfma_f32_16x16x32_bf16 v[56:59], v[164:167], v[188:191], v[56:59]
	v_mfma_f32_16x16x32_bf16 v[44:47], v[156:159], v[196:199], v[44:47]
	v_mfma_f32_16x16x32_bf16 v[40:43], v[164:167], v[196:199], v[40:43]
	v_mfma_f32_16x16x32_bf16 v[28:31], v[156:159], v[204:207], v[28:31]
	v_mfma_f32_16x16x32_bf16 v[24:27], v[164:167], v[204:207], v[24:27]
	v_mfma_f32_16x16x32_bf16 v[12:15], v[156:159], v[212:215], v[12:15]
	v_mfma_f32_16x16x32_bf16 v[8:11], v[164:167], v[212:215], v[8:11]
	s_setprio 0
	s_setprio 1
	v_mfma_f32_16x16x32_bf16 v[52:55], v[168:171], v[184:187], v[52:55]
	v_mfma_f32_16x16x32_bf16 v[48:51], v[176:179], v[184:187], v[48:51]
	v_mfma_f32_16x16x32_bf16 v[36:39], v[168:171], v[192:195], v[36:39]
	v_mfma_f32_16x16x32_bf16 v[32:35], v[176:179], v[192:195], v[32:35]
	v_mfma_f32_16x16x32_bf16 v[20:23], v[168:171], v[200:203], v[20:23]
	v_mfma_f32_16x16x32_bf16 v[16:19], v[176:179], v[200:203], v[16:19]
	v_mfma_f32_16x16x32_bf16 v[4:7], v[168:171], v[208:211], v[4:7]
	v_mfma_f32_16x16x32_bf16 v[0:3], v[176:179], v[208:211], v[0:3]
	v_mfma_f32_16x16x32_bf16 v[52:55], v[172:175], v[188:191], v[52:55]
	v_mfma_f32_16x16x32_bf16 v[48:51], v[180:183], v[188:191], v[48:51]
	v_mfma_f32_16x16x32_bf16 v[36:39], v[172:175], v[196:199], v[36:39]
	v_mfma_f32_16x16x32_bf16 v[32:35], v[180:183], v[196:199], v[32:35]
	v_mfma_f32_16x16x32_bf16 v[20:23], v[172:175], v[204:207], v[20:23]
	v_mfma_f32_16x16x32_bf16 v[16:19], v[180:183], v[204:207], v[16:19]
	v_mfma_f32_16x16x32_bf16 v[4:7], v[172:175], v[212:215], v[4:7]
	v_mfma_f32_16x16x32_bf16 v[0:3], v[180:183], v[212:215], v[0:3]
	s_setprio 0
	s_add_i32 s64, s64, 2
	s_add_u32 s62, s62, 0x100
	s_addc_u32 s63, s63, 0
	s_add_u32 s40, s40, 0x100
	s_addc_u32 s41, s41, 0
	s_cmp_gt_u32 s64, 61
	s_barrier
	s_cbranch_scc0 .LBB0_1150
	s_and_b64 vcc, exec, s[20:21]
	s_cbranch_vccz .LBB0_1153
	s_barrier

.LBB0_1236:
	ds_read_b128 v[162:165], v156
	ds_read_b128 v[166:169], v156 offset:1024
	ds_read_b128 v[170:173], v156 offset:2048
	ds_read_b128 v[174:177], v156 offset:3072
	ds_read_b128 v[178:181], v157
	ds_read_b128 v[182:185], v157 offset:1024
	ds_read_b128 v[186:189], v157 offset:2048
	ds_read_b128 v[190:193], v157 offset:3072
	s_add_u32 s40, s38, 0xfffc0080
	s_addc_u32 s41, s39, -1
	s_cmp_eq_u32 s74, 12
	s_cselect_b32 s43, s9, s41
	s_cselect_b32 s42, s13, s40
	s_cselect_b32 s41, s25, s69
	s_cselect_b32 s40, s27, s68
	v_lshl_add_u64 v[152:153], s[38:39], 0, v[144:145]
	s_add_i32 m0, s45, 0xc000
	ds_read_b128 v[194:197], v158
	ds_read_b128 v[198:201], v158 offset:1024
	ds_read_b128 v[202:205], v158 offset:2048
	ds_read_b128 v[206:209], v158 offset:3072
	ds_read_b128 v[210:213], v158 offset:4096
	ds_read_b128 v[214:217], v158 offset:5120
	ds_read_b128 v[218:221], v158 offset:6144
	ds_read_b128 v[222:225], v158 offset:7168
	global_load_lds_dwordx4 v[152:153], off
	v_lshl_add_u64 v[152:153], s[38:39], 0, v[146:147]
	s_add_i32 m0, s45, 0xe000
	s_nop 0
	global_load_lds_dwordx4 v[152:153], off
	s_waitcnt vmcnt(8)
	s_waitcnt lgkmcnt(0)
	s_barrier
	s_setprio 1
	s_waitcnt lgkmcnt(0)
	v_mfma_f32_16x16x32_bf16 v[124:127], v[162:165], v[194:197], v[124:127]
	v_mfma_f32_16x16x32_bf16 v[120:123], v[170:173], v[194:197], v[120:123]
	v_mfma_f32_16x16x32_bf16 v[108:111], v[162:165], v[202:205], v[108:111]
	v_mfma_f32_16x16x32_bf16 v[104:107], v[170:173], v[202:205], v[104:107]
	v_mfma_f32_16x16x32_bf16 v[92:95], v[162:165], v[210:213], v[92:95]
	v_mfma_f32_16x16x32_bf16 v[88:91], v[170:173], v[210:213], v[88:91]
	v_mfma_f32_16x16x32_bf16 v[76:79], v[162:165], v[218:221], v[76:79]
	v_mfma_f32_16x16x32_bf16 v[72:75], v[170:173], v[218:221], v[72:75]
	v_mfma_f32_16x16x32_bf16 v[124:127], v[166:169], v[198:201], v[124:127]
	v_mfma_f32_16x16x32_bf16 v[120:123], v[174:177], v[198:201], v[120:123]
	v_mfma_f32_16x16x32_bf16 v[108:111], v[166:169], v[206:209], v[108:111]
	v_mfma_f32_16x16x32_bf16 v[104:107], v[174:177], v[206:209], v[104:107]
	v_mfma_f32_16x16x32_bf16 v[92:95], v[166:169], v[214:217], v[92:95]
	v_mfma_f32_16x16x32_bf16 v[88:91], v[174:177], v[214:217], v[88:91]
	v_mfma_f32_16x16x32_bf16 v[76:79], v[166:169], v[222:225], v[76:79]
	v_mfma_f32_16x16x32_bf16 v[72:75], v[174:177], v[222:225], v[72:75]
	s_setprio 0
	s_setprio 1
	v_mfma_f32_16x16x32_bf16 v[116:119], v[178:181], v[194:197], v[116:119]
	v_mfma_f32_16x16x32_bf16 v[112:115], v[186:189], v[194:197], v[112:115]
	v_mfma_f32_16x16x32_bf16 v[100:103], v[178:181], v[202:205], v[100:103]
	v_mfma_f32_16x16x32_bf16 v[96:99], v[186:189], v[202:205], v[96:99]
	v_mfma_f32_16x16x32_bf16 v[84:87], v[178:181], v[210:213], v[84:87]
	v_mfma_f32_16x16x32_bf16 v[80:83], v[186:189], v[210:213], v[80:83]
	v_mfma_f32_16x16x32_bf16 v[68:71], v[178:181], v[218:221], v[68:71]
	v_mfma_f32_16x16x32_bf16 v[64:67], v[186:189], v[218:221], v[64:67]
	v_mfma_f32_16x16x32_bf16 v[116:119], v[182:185], v[198:201], v[116:119]
	v_mfma_f32_16x16x32_bf16 v[112:115], v[190:193], v[198:201], v[112:115]
	v_mfma_f32_16x16x32_bf16 v[100:103], v[182:185], v[206:209], v[100:103]
	v_mfma_f32_16x16x32_bf16 v[96:99], v[190:193], v[206:209], v[96:99]
	v_mfma_f32_16x16x32_bf16 v[84:87], v[182:185], v[214:217], v[84:87]
	v_mfma_f32_16x16x32_bf16 v[80:83], v[190:193], v[214:217], v[80:83]
	v_mfma_f32_16x16x32_bf16 v[68:71], v[182:185], v[222:225], v[68:71]
	v_mfma_f32_16x16x32_bf16 v[64:67], v[190:193], v[222:225], v[64:67]
	s_setprio 0
	s_barrier
	s_add_i32 s75, s66, s44
	v_lshl_add_u64 v[152:153], s[40:41], 0, v[130:131]
	s_mov_b32 m0, s75
	ds_read_b128 v[194:197], v158 offset:16384
	ds_read_b128 v[198:201], v158 offset:17408
	ds_read_b128 v[202:205], v158 offset:18432
	ds_read_b128 v[206:209], v158 offset:19456
	ds_read_b128 v[210:213], v158 offset:20480
	ds_read_b128 v[214:217], v158 offset:21504
	ds_read_b128 v[218:221], v158 offset:22528
	ds_read_b128 v[222:225], v158 offset:23552
	global_load_lds_dwordx4 v[152:153], off
	s_add_i32 m0, s75, 0x2000
	s_add_u32 s76, s40, 0x40000
	v_lshl_add_u64 v[226:227], s[40:41], 0, v[134:135]
	s_addc_u32 s77, s41, 0
	s_add_i32 s75, s67, s44
	global_load_lds_dwordx4 v[226:227], off
	v_lshl_add_u64 v[228:229], s[76:77], 0, v[130:131]
	s_mov_b32 m0, s75
	v_lshl_add_u64 v[230:231], s[42:43], 0, v[132:133]
	global_load_lds_dwordx4 v[228:229], off
	v_lshl_add_u64 v[228:229], s[76:77], 0, v[134:135]
	s_add_i32 m0, s75, 0x2000
	s_nop 0
	global_load_lds_dwordx4 v[228:229], off
	v_lshl_add_u64 v[228:229], s[42:43], 0, v[128:129]
	s_mov_b32 m0, s45
	s_nop 0
	global_load_lds_dwordx4 v[228:229], off
	s_mov_b32 m0, s46
	s_nop 0
	global_load_lds_dwordx4 v[230:231], off
	s_waitcnt vmcnt(8)
	s_waitcnt lgkmcnt(0)
	s_barrier
	s_setprio 1
	s_waitcnt lgkmcnt(0)
	v_mfma_f32_16x16x32_bf16 v[60:63], v[162:165], v[194:197], v[60:63]
	v_mfma_f32_16x16x32_bf16 v[56:59], v[170:173], v[194:197], v[56:59]
	v_mfma_f32_16x16x32_bf16 v[44:47], v[162:165], v[202:205], v[44:47]
	v_mfma_f32_16x16x32_bf16 v[40:43], v[170:173], v[202:205], v[40:43]
	v_mfma_f32_16x16x32_bf16 v[28:31], v[162:165], v[210:213], v[28:31]
	v_mfma_f32_16x16x32_bf16 v[24:27], v[170:173], v[210:213], v[24:27]
	v_mfma_f32_16x16x32_bf16 v[12:15], v[162:165], v[218:221], v[12:15]
	v_mfma_f32_16x16x32_bf16 v[8:11], v[170:173], v[218:221], v[8:11]
	v_mfma_f32_16x16x32_bf16 v[60:63], v[166:169], v[198:201], v[60:63]
	v_mfma_f32_16x16x32_bf16 v[56:59], v[174:177], v[198:201], v[56:59]
	v_mfma_f32_16x16x32_bf16 v[44:47], v[166:169], v[206:209], v[44:47]
	v_mfma_f32_16x16x32_bf16 v[40:43], v[174:177], v[206:209], v[40:43]
	v_mfma_f32_16x16x32_bf16 v[28:31], v[166:169], v[214:217], v[28:31]
	v_mfma_f32_16x16x32_bf16 v[24:27], v[174:177], v[214:217], v[24:27]
	v_mfma_f32_16x16x32_bf16 v[12:15], v[166:169], v[222:225], v[12:15]
	v_mfma_f32_16x16x32_bf16 v[8:11], v[174:177], v[222:225], v[8:11]
	s_setprio 0
	s_setprio 1
	v_mfma_f32_16x16x32_bf16 v[52:55], v[178:181], v[194:197], v[52:55]
	v_mfma_f32_16x16x32_bf16 v[48:51], v[186:189], v[194:197], v[48:51]
	v_mfma_f32_16x16x32_bf16 v[36:39], v[178:181], v[202:205], v[36:39]
	v_mfma_f32_16x16x32_bf16 v[32:35], v[186:189], v[202:205], v[32:35]
	v_mfma_f32_16x16x32_bf16 v[20:23], v[178:181], v[210:213], v[20:23]
	v_mfma_f32_16x16x32_bf16 v[16:19], v[186:189], v[210:213], v[16:19]
	v_mfma_f32_16x16x32_bf16 v[4:7], v[178:181], v[218:221], v[4:7]
	v_mfma_f32_16x16x32_bf16 v[0:3], v[186:189], v[218:221], v[0:3]
	v_mfma_f32_16x16x32_bf16 v[52:55], v[182:185], v[198:201], v[52:55]
	v_mfma_f32_16x16x32_bf16 v[48:51], v[190:193], v[198:201], v[48:51]
	v_mfma_f32_16x16x32_bf16 v[36:39], v[182:185], v[206:209], v[36:39]
	v_mfma_f32_16x16x32_bf16 v[32:35], v[190:193], v[206:209], v[32:35]
	v_mfma_f32_16x16x32_bf16 v[20:23], v[182:185], v[214:217], v[20:23]
	v_mfma_f32_16x16x32_bf16 v[16:19], v[190:193], v[214:217], v[16:19]
	v_mfma_f32_16x16x32_bf16 v[4:7], v[182:185], v[222:225], v[4:7]
	v_mfma_f32_16x16x32_bf16 v[0:3], v[190:193], v[222:225], v[0:3]
	s_setprio 0
	s_barrier
	s_add_i32 s75, 0, 0x18000
	v_add_u32_e32 v136, s75, v155
	s_add_i32 s76, 0, 0x1c000
	ds_read_b128 v[162:165], v136
	ds_read_b128 v[166:169], v136 offset:1024
	ds_read_b128 v[170:173], v136 offset:2048
	ds_read_b128 v[174:177], v136 offset:3072
	v_add_u32_e32 v136, s76, v155
	ds_read_b128 v[178:181], v136
	ds_read_b128 v[182:185], v136 offset:1024
	ds_read_b128 v[186:189], v136 offset:2048
	ds_read_b128 v[190:193], v136 offset:3072
	s_add_u32 s42, s42, 0x40000
	s_addc_u32 s43, s43, 0
	s_mov_b32 m0, s47
	v_lshl_add_u64 v[232:233], s[42:43], 0, v[128:129]
	ds_read_b128 v[194:197], v158 offset:32768
	ds_read_b128 v[198:201], v158 offset:33792
	ds_read_b128 v[202:205], v158 offset:34816
	ds_read_b128 v[206:209], v158 offset:35840
	ds_read_b128 v[210:213], v158 offset:36864
	ds_read_b128 v[214:217], v158 offset:37888
	ds_read_b128 v[218:221], v158 offset:38912
	ds_read_b128 v[222:225], v158 offset:39936
	global_load_lds_dwordx4 v[232:233], off
	v_lshl_add_u64 v[232:233], s[42:43], 0, v[132:133]
	s_mov_b32 m0, s52
	s_nop 0
	global_load_lds_dwordx4 v[232:233], off
	s_waitcnt vmcnt(8)
	s_waitcnt lgkmcnt(0)
	s_barrier
	s_setprio 1
	s_waitcnt lgkmcnt(0)
	v_mfma_f32_16x16x32_bf16 v[124:127], v[162:165], v[194:197], v[124:127]
	v_mfma_f32_16x16x32_bf16 v[120:123], v[170:173], v[194:197], v[120:123]
	v_mfma_f32_16x16x32_bf16 v[108:111], v[162:165], v[202:205], v[108:111]
	v_mfma_f32_16x16x32_bf16 v[104:107], v[170:173], v[202:205], v[104:107]
	v_mfma_f32_16x16x32_bf16 v[92:95], v[162:165], v[210:213], v[92:95]
	v_mfma_f32_16x16x32_bf16 v[88:91], v[170:173], v[210:213], v[88:91]
	v_mfma_f32_16x16x32_bf16 v[76:79], v[162:165], v[218:221], v[76:79]
	v_mfma_f32_16x16x32_bf16 v[72:75], v[170:173], v[218:221], v[72:75]
	v_mfma_f32_16x16x32_bf16 v[124:127], v[166:169], v[198:201], v[124:127]
	v_mfma_f32_16x16x32_bf16 v[120:123], v[174:177], v[198:201], v[120:123]
	v_mfma_f32_16x16x32_bf16 v[108:111], v[166:169], v[206:209], v[108:111]
	v_mfma_f32_16x16x32_bf16 v[104:107], v[174:177], v[206:209], v[104:107]
	v_mfma_f32_16x16x32_bf16 v[92:95], v[166:169], v[214:217], v[92:95]
	v_mfma_f32_16x16x32_bf16 v[88:91], v[174:177], v[214:217], v[88:91]
	v_mfma_f32_16x16x32_bf16 v[76:79], v[166:169], v[222:225], v[76:79]
	v_mfma_f32_16x16x32_bf16 v[72:75], v[174:177], v[222:225], v[72:75]
	s_setprio 0
	s_setprio 1
	v_mfma_f32_16x16x32_bf16 v[116:119], v[178:181], v[194:197], v[116:119]
	v_mfma_f32_16x16x32_bf16 v[112:115], v[186:189], v[194:197], v[112:115]
	v_mfma_f32_16x16x32_bf16 v[100:103], v[178:181], v[202:205], v[100:103]
	v_mfma_f32_16x16x32_bf16 v[96:99], v[186:189], v[202:205], v[96:99]
	v_mfma_f32_16x16x32_bf16 v[84:87], v[178:181], v[210:213], v[84:87]
	v_mfma_f32_16x16x32_bf16 v[80:83], v[186:189], v[210:213], v[80:83]
	v_mfma_f32_16x16x32_bf16 v[68:71], v[178:181], v[218:221], v[68:71]
	v_mfma_f32_16x16x32_bf16 v[64:67], v[186:189], v[218:221], v[64:67]
	v_mfma_f32_16x16x32_bf16 v[116:119], v[182:185], v[198:201], v[116:119]
	v_mfma_f32_16x16x32_bf16 v[112:115], v[190:193], v[198:201], v[112:115]
	v_mfma_f32_16x16x32_bf16 v[100:103], v[182:185], v[206:209], v[100:103]
	v_mfma_f32_16x16x32_bf16 v[96:99], v[190:193], v[206:209], v[96:99]
	v_mfma_f32_16x16x32_bf16 v[84:87], v[182:185], v[214:217], v[84:87]
	v_mfma_f32_16x16x32_bf16 v[80:83], v[190:193], v[214:217], v[80:83]
	v_mfma_f32_16x16x32_bf16 v[68:71], v[182:185], v[222:225], v[68:71]
	v_mfma_f32_16x16x32_bf16 v[64:67], v[190:193], v[222:225], v[64:67]
	s_setprio 0
	s_barrier
	s_add_i32 s42, s75, s44
	v_lshl_add_u64 v[152:153], v[152:153], 0, s[18:19]
	s_mov_b32 m0, s42
	ds_read_b128 v[194:197], v158 offset:49152
	ds_read_b128 v[198:201], v158 offset:50176
	ds_read_b128 v[202:205], v158 offset:51200
	ds_read_b128 v[206:209], v158 offset:52224
	ds_read_b128 v[210:213], v158 offset:53248
	ds_read_b128 v[214:217], v158 offset:54272
	ds_read_b128 v[218:221], v158 offset:55296
	ds_read_b128 v[222:225], v158 offset:56320
	global_load_lds_dwordx4 v[152:153], off
	s_add_i32 m0, s42, 0x2000
	s_add_u32 s40, s40, 0x40080
	v_lshl_add_u64 v[152:153], v[226:227], 0, s[18:19]
	s_addc_u32 s41, s41, 0
	s_add_i32 s42, s76, s44
	global_load_lds_dwordx4 v[152:153], off
	v_lshl_add_u64 v[152:153], s[40:41], 0, v[130:131]
	s_mov_b32 m0, s42
	s_nop 0
	global_load_lds_dwordx4 v[152:153], off
	v_lshl_add_u64 v[152:153], s[40:41], 0, v[134:135]
	s_add_i32 m0, s42, 0x2000
	s_nop 0
	global_load_lds_dwordx4 v[152:153], off
	v_lshl_add_u64 v[152:153], v[228:229], 0, s[18:19]
	s_mov_b32 m0, s62
	s_nop 0
	global_load_lds_dwordx4 v[152:153], off
	v_lshl_add_u64 v[152:153], v[230:231], 0, s[18:19]
	s_mov_b32 m0, s63
	s_nop 0
	global_load_lds_dwordx4 v[152:153], off
	s_waitcnt vmcnt(8)
	s_waitcnt lgkmcnt(0)
	s_barrier
	s_setprio 1
	s_waitcnt lgkmcnt(0)
	v_mfma_f32_16x16x32_bf16 v[60:63], v[162:165], v[194:197], v[60:63]
	v_mfma_f32_16x16x32_bf16 v[56:59], v[170:173], v[194:197], v[56:59]
	v_mfma_f32_16x16x32_bf16 v[44:47], v[162:165], v[202:205], v[44:47]
	v_mfma_f32_16x16x32_bf16 v[40:43], v[170:173], v[202:205], v[40:43]
	v_mfma_f32_16x16x32_bf16 v[28:31], v[162:165], v[210:213], v[28:31]
	v_mfma_f32_16x16x32_bf16 v[24:27], v[170:173], v[210:213], v[24:27]
	v_mfma_f32_16x16x32_bf16 v[12:15], v[162:165], v[218:221], v[12:15]
	v_mfma_f32_16x16x32_bf16 v[8:11], v[170:173], v[218:221], v[8:11]
	v_mfma_f32_16x16x32_bf16 v[60:63], v[166:169], v[198:201], v[60:63]
	v_mfma_f32_16x16x32_bf16 v[56:59], v[174:177], v[198:201], v[56:59]
	v_mfma_f32_16x16x32_bf16 v[44:47], v[166:169], v[206:209], v[44:47]
	v_mfma_f32_16x16x32_bf16 v[40:43], v[174:177], v[206:209], v[40:43]
	v_mfma_f32_16x16x32_bf16 v[28:31], v[166:169], v[214:217], v[28:31]
	v_mfma_f32_16x16x32_bf16 v[24:27], v[174:177], v[214:217], v[24:27]
	v_mfma_f32_16x16x32_bf16 v[12:15], v[166:169], v[222:225], v[12:15]
	v_mfma_f32_16x16x32_bf16 v[8:11], v[174:177], v[222:225], v[8:11]
	s_setprio 0
	s_setprio 1
	v_mfma_f32_16x16x32_bf16 v[52:55], v[178:181], v[194:197], v[52:55]
	v_mfma_f32_16x16x32_bf16 v[48:51], v[186:189], v[194:197], v[48:51]
	v_mfma_f32_16x16x32_bf16 v[36:39], v[178:181], v[202:205], v[36:39]
	v_mfma_f32_16x16x32_bf16 v[32:35], v[186:189], v[202:205], v[32:35]
	v_mfma_f32_16x16x32_bf16 v[20:23], v[178:181], v[210:213], v[20:23]
	v_mfma_f32_16x16x32_bf16 v[16:19], v[186:189], v[210:213], v[16:19]
	v_mfma_f32_16x16x32_bf16 v[4:7], v[178:181], v[218:221], v[4:7]
	v_mfma_f32_16x16x32_bf16 v[0:3], v[186:189], v[218:221], v[0:3]
	v_mfma_f32_16x16x32_bf16 v[52:55], v[182:185], v[198:201], v[52:55]
	v_mfma_f32_16x16x32_bf16 v[48:51], v[190:193], v[198:201], v[48:51]
	v_mfma_f32_16x16x32_bf16 v[36:39], v[182:185], v[206:209], v[36:39]
	v_mfma_f32_16x16x32_bf16 v[32:35], v[190:193], v[206:209], v[32:35]
	v_mfma_f32_16x16x32_bf16 v[20:23], v[182:185], v[214:217], v[20:23]
	v_mfma_f32_16x16x32_bf16 v[16:19], v[190:193], v[214:217], v[16:19]
	v_mfma_f32_16x16x32_bf16 v[4:7], v[182:185], v[222:225], v[4:7]
	v_mfma_f32_16x16x32_bf16 v[0:3], v[190:193], v[222:225], v[0:3]
	s_setprio 0
	s_add_i32 s74, s74, 2
	s_add_u32 s38, s38, 0x100
	s_addc_u32 s39, s39, 0
	s_add_u32 s68, s68, 0x100
	s_addc_u32 s69, s69, 0
	s_cmp_gt_u32 s74, 13
	s_barrier
	s_cbranch_scc0 .LBB0_1236
	s_and_b64 vcc, exec, s[20:21]
	s_cbranch_vccz .LBB0_1239
	s_barrier

.LBB0_1705:
	ds_read_b128 v[144:147], v151
	ds_read_b128 v[156:159], v151 offset:1024
	ds_read_b128 v[160:163], v151 offset:2048
	ds_read_b128 v[164:167], v151 offset:3072
	ds_read_b128 v[168:171], v152
	ds_read_b128 v[172:175], v152 offset:1024
	ds_read_b128 v[176:179], v152 offset:2048
	ds_read_b128 v[180:183], v152 offset:3072
	s_add_u32 s30, s28, 0xfffc0080
	s_addc_u32 s31, s29, -1
	s_cmp_eq_u32 s59, 12
	s_cselect_b32 s37, s21, s31
	s_cselect_b32 s36, s55, s30
	s_cselect_b32 s31, s19, s58
	s_cselect_b32 s30, s56, s57
	v_lshl_add_u64 v[216:217], s[28:29], 0, v[138:139]
	s_add_i32 m0, s27, 0xc000
	ds_read_b128 v[184:187], v153
	ds_read_b128 v[188:191], v153 offset:1024
	ds_read_b128 v[192:195], v153 offset:2048
	ds_read_b128 v[196:199], v153 offset:3072
	ds_read_b128 v[200:203], v153 offset:4096
	ds_read_b128 v[204:207], v153 offset:5120
	ds_read_b128 v[208:211], v153 offset:6144
	ds_read_b128 v[212:215], v153 offset:7168
	global_load_lds_dwordx4 v[216:217], off
	v_lshl_add_u64 v[216:217], s[28:29], 0, v[136:137]
	s_add_i32 m0, s27, 0xe000
	s_nop 0
	global_load_lds_dwordx4 v[216:217], off
	s_waitcnt vmcnt(8)
	s_waitcnt lgkmcnt(0)
	s_barrier
	s_setprio 1
	s_waitcnt lgkmcnt(0)
	v_mfma_f32_16x16x32_bf16 v[124:127], v[144:147], v[184:187], v[124:127]
	v_mfma_f32_16x16x32_bf16 v[120:123], v[160:163], v[184:187], v[120:123]
	v_mfma_f32_16x16x32_bf16 v[108:111], v[144:147], v[192:195], v[108:111]
	v_mfma_f32_16x16x32_bf16 v[104:107], v[160:163], v[192:195], v[104:107]
	v_mfma_f32_16x16x32_bf16 v[92:95], v[144:147], v[200:203], v[92:95]
	v_mfma_f32_16x16x32_bf16 v[88:91], v[160:163], v[200:203], v[88:91]
	v_mfma_f32_16x16x32_bf16 v[76:79], v[144:147], v[208:211], v[76:79]
	v_mfma_f32_16x16x32_bf16 v[72:75], v[160:163], v[208:211], v[72:75]
	v_mfma_f32_16x16x32_bf16 v[124:127], v[156:159], v[188:191], v[124:127]
	v_mfma_f32_16x16x32_bf16 v[120:123], v[164:167], v[188:191], v[120:123]
	v_mfma_f32_16x16x32_bf16 v[108:111], v[156:159], v[196:199], v[108:111]
	v_mfma_f32_16x16x32_bf16 v[104:107], v[164:167], v[196:199], v[104:107]
	v_mfma_f32_16x16x32_bf16 v[92:95], v[156:159], v[204:207], v[92:95]
	v_mfma_f32_16x16x32_bf16 v[88:91], v[164:167], v[204:207], v[88:91]
	v_mfma_f32_16x16x32_bf16 v[76:79], v[156:159], v[212:215], v[76:79]
	v_mfma_f32_16x16x32_bf16 v[72:75], v[164:167], v[212:215], v[72:75]
	s_setprio 0
	s_setprio 1
	v_mfma_f32_16x16x32_bf16 v[116:119], v[168:171], v[184:187], v[116:119]
	v_mfma_f32_16x16x32_bf16 v[112:115], v[176:179], v[184:187], v[112:115]
	v_mfma_f32_16x16x32_bf16 v[100:103], v[168:171], v[192:195], v[100:103]
	v_mfma_f32_16x16x32_bf16 v[96:99], v[176:179], v[192:195], v[96:99]
	v_mfma_f32_16x16x32_bf16 v[84:87], v[168:171], v[200:203], v[84:87]
	v_mfma_f32_16x16x32_bf16 v[80:83], v[176:179], v[200:203], v[80:83]
	v_mfma_f32_16x16x32_bf16 v[68:71], v[168:171], v[208:211], v[68:71]
	v_mfma_f32_16x16x32_bf16 v[64:67], v[176:179], v[208:211], v[64:67]
	v_mfma_f32_16x16x32_bf16 v[116:119], v[172:175], v[188:191], v[116:119]
	v_mfma_f32_16x16x32_bf16 v[112:115], v[180:183], v[188:191], v[112:115]
	v_mfma_f32_16x16x32_bf16 v[100:103], v[172:175], v[196:199], v[100:103]
	v_mfma_f32_16x16x32_bf16 v[96:99], v[180:183], v[196:199], v[96:99]
	v_mfma_f32_16x16x32_bf16 v[84:87], v[172:175], v[204:207], v[84:87]
	v_mfma_f32_16x16x32_bf16 v[80:83], v[180:183], v[204:207], v[80:83]
	v_mfma_f32_16x16x32_bf16 v[68:71], v[172:175], v[212:215], v[68:71]
	v_mfma_f32_16x16x32_bf16 v[64:67], v[180:183], v[212:215], v[64:67]
	s_setprio 0
	s_barrier
	s_add_i32 s60, s47, s38
	v_lshl_add_u64 v[216:217], s[30:31], 0, v[130:131]
	s_mov_b32 m0, s60
	ds_read_b128 v[184:187], v153 offset:16384
	ds_read_b128 v[188:191], v153 offset:17408
	ds_read_b128 v[192:195], v153 offset:18432
	ds_read_b128 v[196:199], v153 offset:19456
	ds_read_b128 v[200:203], v153 offset:20480
	ds_read_b128 v[204:207], v153 offset:21504
	ds_read_b128 v[208:211], v153 offset:22528
	ds_read_b128 v[212:215], v153 offset:23552
	global_load_lds_dwordx4 v[216:217], off
	s_add_i32 m0, s60, 0x2000
	s_add_u32 s60, s30, 0x40000
	v_lshl_add_u64 v[218:219], s[30:31], 0, v[134:135]
	s_addc_u32 s61, s31, 0
	s_add_i32 s62, s52, s38
	global_load_lds_dwordx4 v[218:219], off
	v_lshl_add_u64 v[220:221], s[60:61], 0, v[130:131]
	s_mov_b32 m0, s62
	v_lshl_add_u64 v[222:223], s[36:37], 0, v[132:133]
	global_load_lds_dwordx4 v[220:221], off
	v_lshl_add_u64 v[220:221], s[60:61], 0, v[134:135]
	s_add_i32 m0, s62, 0x2000
	s_nop 0
	global_load_lds_dwordx4 v[220:221], off
	v_lshl_add_u64 v[220:221], s[36:37], 0, v[128:129]
	s_mov_b32 m0, s27
	s_nop 0
	global_load_lds_dwordx4 v[220:221], off
	s_mov_b32 m0, s39
	s_nop 0
	global_load_lds_dwordx4 v[222:223], off
	s_waitcnt vmcnt(8)
	s_waitcnt lgkmcnt(0)
	s_barrier
	s_setprio 1
	s_waitcnt lgkmcnt(0)
	v_mfma_f32_16x16x32_bf16 v[60:63], v[144:147], v[184:187], v[60:63]
	v_mfma_f32_16x16x32_bf16 v[56:59], v[160:163], v[184:187], v[56:59]
	v_mfma_f32_16x16x32_bf16 v[44:47], v[144:147], v[192:195], v[44:47]
	v_mfma_f32_16x16x32_bf16 v[40:43], v[160:163], v[192:195], v[40:43]
	v_mfma_f32_16x16x32_bf16 v[28:31], v[144:147], v[200:203], v[28:31]
	v_mfma_f32_16x16x32_bf16 v[24:27], v[160:163], v[200:203], v[24:27]
	v_mfma_f32_16x16x32_bf16 v[12:15], v[144:147], v[208:211], v[12:15]
	v_mfma_f32_16x16x32_bf16 v[8:11], v[160:163], v[208:211], v[8:11]
	v_mfma_f32_16x16x32_bf16 v[60:63], v[156:159], v[188:191], v[60:63]
	v_mfma_f32_16x16x32_bf16 v[56:59], v[164:167], v[188:191], v[56:59]
	v_mfma_f32_16x16x32_bf16 v[44:47], v[156:159], v[196:199], v[44:47]
	v_mfma_f32_16x16x32_bf16 v[40:43], v[164:167], v[196:199], v[40:43]
	v_mfma_f32_16x16x32_bf16 v[28:31], v[156:159], v[204:207], v[28:31]
	v_mfma_f32_16x16x32_bf16 v[24:27], v[164:167], v[204:207], v[24:27]
	v_mfma_f32_16x16x32_bf16 v[12:15], v[156:159], v[212:215], v[12:15]
	v_mfma_f32_16x16x32_bf16 v[8:11], v[164:167], v[212:215], v[8:11]
	s_setprio 0
	s_setprio 1
	v_mfma_f32_16x16x32_bf16 v[52:55], v[168:171], v[184:187], v[52:55]
	v_mfma_f32_16x16x32_bf16 v[48:51], v[176:179], v[184:187], v[48:51]
	v_mfma_f32_16x16x32_bf16 v[36:39], v[168:171], v[192:195], v[36:39]
	v_mfma_f32_16x16x32_bf16 v[32:35], v[176:179], v[192:195], v[32:35]
	v_mfma_f32_16x16x32_bf16 v[20:23], v[168:171], v[200:203], v[20:23]
	v_mfma_f32_16x16x32_bf16 v[16:19], v[176:179], v[200:203], v[16:19]
	v_mfma_f32_16x16x32_bf16 v[4:7], v[168:171], v[208:211], v[4:7]
	v_mfma_f32_16x16x32_bf16 v[0:3], v[176:179], v[208:211], v[0:3]
	v_mfma_f32_16x16x32_bf16 v[52:55], v[172:175], v[188:191], v[52:55]
	v_mfma_f32_16x16x32_bf16 v[48:51], v[180:183], v[188:191], v[48:51]
	v_mfma_f32_16x16x32_bf16 v[36:39], v[172:175], v[196:199], v[36:39]
	v_mfma_f32_16x16x32_bf16 v[32:35], v[180:183], v[196:199], v[32:35]
	v_mfma_f32_16x16x32_bf16 v[20:23], v[172:175], v[204:207], v[20:23]
	v_mfma_f32_16x16x32_bf16 v[16:19], v[180:183], v[204:207], v[16:19]
	v_mfma_f32_16x16x32_bf16 v[4:7], v[172:175], v[212:215], v[4:7]
	v_mfma_f32_16x16x32_bf16 v[0:3], v[180:183], v[212:215], v[0:3]
	s_setprio 0
	s_barrier
	s_add_i32 s60, 0, 0x18000
	v_add_u32_e32 v155, s60, v149
	s_add_i32 s61, 0, 0x1c000
	ds_read_b128 v[144:147], v155
	ds_read_b128 v[156:159], v155 offset:1024
	ds_read_b128 v[160:163], v155 offset:2048
	ds_read_b128 v[164:167], v155 offset:3072
	v_add_u32_e32 v155, s61, v149
	ds_read_b128 v[168:171], v155
	ds_read_b128 v[172:175], v155 offset:1024
	ds_read_b128 v[176:179], v155 offset:2048
	ds_read_b128 v[180:183], v155 offset:3072
	s_add_u32 s36, s36, 0x40000
	s_addc_u32 s37, s37, 0
	s_mov_b32 m0, s40
	v_lshl_add_u64 v[224:225], s[36:37], 0, v[128:129]
	ds_read_b128 v[184:187], v153 offset:32768
	ds_read_b128 v[188:191], v153 offset:33792
	ds_read_b128 v[192:195], v153 offset:34816
	ds_read_b128 v[196:199], v153 offset:35840
	ds_read_b128 v[200:203], v153 offset:36864
	ds_read_b128 v[204:207], v153 offset:37888
	ds_read_b128 v[208:211], v153 offset:38912
	ds_read_b128 v[212:215], v153 offset:39936
	global_load_lds_dwordx4 v[224:225], off
	v_lshl_add_u64 v[224:225], s[36:37], 0, v[132:133]
	s_mov_b32 m0, s41
	s_nop 0
	global_load_lds_dwordx4 v[224:225], off
	s_waitcnt vmcnt(8)
	s_waitcnt lgkmcnt(0)
	s_barrier
	s_setprio 1
	s_waitcnt lgkmcnt(0)
	v_mfma_f32_16x16x32_bf16 v[124:127], v[144:147], v[184:187], v[124:127]
	v_mfma_f32_16x16x32_bf16 v[120:123], v[160:163], v[184:187], v[120:123]
	v_mfma_f32_16x16x32_bf16 v[108:111], v[144:147], v[192:195], v[108:111]
	v_mfma_f32_16x16x32_bf16 v[104:107], v[160:163], v[192:195], v[104:107]
	v_mfma_f32_16x16x32_bf16 v[92:95], v[144:147], v[200:203], v[92:95]
	v_mfma_f32_16x16x32_bf16 v[88:91], v[160:163], v[200:203], v[88:91]
	v_mfma_f32_16x16x32_bf16 v[76:79], v[144:147], v[208:211], v[76:79]
	v_mfma_f32_16x16x32_bf16 v[72:75], v[160:163], v[208:211], v[72:75]
	v_mfma_f32_16x16x32_bf16 v[124:127], v[156:159], v[188:191], v[124:127]
	v_mfma_f32_16x16x32_bf16 v[120:123], v[164:167], v[188:191], v[120:123]
	v_mfma_f32_16x16x32_bf16 v[108:111], v[156:159], v[196:199], v[108:111]
	v_mfma_f32_16x16x32_bf16 v[104:107], v[164:167], v[196:199], v[104:107]
	v_mfma_f32_16x16x32_bf16 v[92:95], v[156:159], v[204:207], v[92:95]
	v_mfma_f32_16x16x32_bf16 v[88:91], v[164:167], v[204:207], v[88:91]
	v_mfma_f32_16x16x32_bf16 v[76:79], v[156:159], v[212:215], v[76:79]
	v_mfma_f32_16x16x32_bf16 v[72:75], v[164:167], v[212:215], v[72:75]
	s_setprio 0
	s_setprio 1
	v_mfma_f32_16x16x32_bf16 v[116:119], v[168:171], v[184:187], v[116:119]
	v_mfma_f32_16x16x32_bf16 v[112:115], v[176:179], v[184:187], v[112:115]
	v_mfma_f32_16x16x32_bf16 v[100:103], v[168:171], v[192:195], v[100:103]
	v_mfma_f32_16x16x32_bf16 v[96:99], v[176:179], v[192:195], v[96:99]
	v_mfma_f32_16x16x32_bf16 v[84:87], v[168:171], v[200:203], v[84:87]
	v_mfma_f32_16x16x32_bf16 v[80:83], v[176:179], v[200:203], v[80:83]
	v_mfma_f32_16x16x32_bf16 v[68:71], v[168:171], v[208:211], v[68:71]
	v_mfma_f32_16x16x32_bf16 v[64:67], v[176:179], v[208:211], v[64:67]
	v_mfma_f32_16x16x32_bf16 v[116:119], v[172:175], v[188:191], v[116:119]
	v_mfma_f32_16x16x32_bf16 v[112:115], v[180:183], v[188:191], v[112:115]
	v_mfma_f32_16x16x32_bf16 v[100:103], v[172:175], v[196:199], v[100:103]
	v_mfma_f32_16x16x32_bf16 v[96:99], v[180:183], v[196:199], v[96:99]
	v_mfma_f32_16x16x32_bf16 v[84:87], v[172:175], v[204:207], v[84:87]
	v_mfma_f32_16x16x32_bf16 v[80:83], v[180:183], v[204:207], v[80:83]
	v_mfma_f32_16x16x32_bf16 v[68:71], v[172:175], v[212:215], v[68:71]
	v_mfma_f32_16x16x32_bf16 v[64:67], v[180:183], v[212:215], v[64:67]
	s_setprio 0
	s_barrier
	s_add_i32 s36, s60, s38
	v_lshl_add_u64 v[216:217], v[216:217], 0, s[14:15]
	s_mov_b32 m0, s36
	ds_read_b128 v[184:187], v153 offset:49152
	ds_read_b128 v[188:191], v153 offset:50176
	ds_read_b128 v[192:195], v153 offset:51200
	ds_read_b128 v[196:199], v153 offset:52224
	ds_read_b128 v[200:203], v153 offset:53248
	ds_read_b128 v[204:207], v153 offset:54272
	ds_read_b128 v[208:211], v153 offset:55296
	ds_read_b128 v[212:215], v153 offset:56320
	global_load_lds_dwordx4 v[216:217], off
	s_add_i32 m0, s36, 0x2000
	s_add_u32 s30, s30, 0x40080
	v_lshl_add_u64 v[216:217], v[218:219], 0, s[14:15]
	s_addc_u32 s31, s31, 0
	s_add_i32 s36, s61, s38
	global_load_lds_dwordx4 v[216:217], off
	v_lshl_add_u64 v[216:217], s[30:31], 0, v[130:131]
	s_mov_b32 m0, s36
	s_nop 0
	global_load_lds_dwordx4 v[216:217], off
	v_lshl_add_u64 v[216:217], s[30:31], 0, v[134:135]
	s_add_i32 m0, s36, 0x2000
	s_nop 0
	global_load_lds_dwordx4 v[216:217], off
	v_lshl_add_u64 v[216:217], v[220:221], 0, s[14:15]
	s_mov_b32 m0, s43
	s_nop 0
	global_load_lds_dwordx4 v[216:217], off
	v_lshl_add_u64 v[216:217], v[222:223], 0, s[14:15]
	s_mov_b32 m0, s44
	s_nop 0
	global_load_lds_dwordx4 v[216:217], off
	s_waitcnt vmcnt(8)
	s_waitcnt lgkmcnt(0)
	s_barrier
	s_setprio 1
	s_waitcnt lgkmcnt(0)
	v_mfma_f32_16x16x32_bf16 v[60:63], v[144:147], v[184:187], v[60:63]
	v_mfma_f32_16x16x32_bf16 v[56:59], v[160:163], v[184:187], v[56:59]
	v_mfma_f32_16x16x32_bf16 v[44:47], v[144:147], v[192:195], v[44:47]
	v_mfma_f32_16x16x32_bf16 v[40:43], v[160:163], v[192:195], v[40:43]
	v_mfma_f32_16x16x32_bf16 v[28:31], v[144:147], v[200:203], v[28:31]
	v_mfma_f32_16x16x32_bf16 v[24:27], v[160:163], v[200:203], v[24:27]
	v_mfma_f32_16x16x32_bf16 v[12:15], v[144:147], v[208:211], v[12:15]
	v_mfma_f32_16x16x32_bf16 v[8:11], v[160:163], v[208:211], v[8:11]
	v_mfma_f32_16x16x32_bf16 v[60:63], v[156:159], v[188:191], v[60:63]
	v_mfma_f32_16x16x32_bf16 v[56:59], v[164:167], v[188:191], v[56:59]
	v_mfma_f32_16x16x32_bf16 v[44:47], v[156:159], v[196:199], v[44:47]
	v_mfma_f32_16x16x32_bf16 v[40:43], v[164:167], v[196:199], v[40:43]
	v_mfma_f32_16x16x32_bf16 v[28:31], v[156:159], v[204:207], v[28:31]
	v_mfma_f32_16x16x32_bf16 v[24:27], v[164:167], v[204:207], v[24:27]
	v_mfma_f32_16x16x32_bf16 v[12:15], v[156:159], v[212:215], v[12:15]
	v_mfma_f32_16x16x32_bf16 v[8:11], v[164:167], v[212:215], v[8:11]
	s_setprio 0
	s_setprio 1
	v_mfma_f32_16x16x32_bf16 v[52:55], v[168:171], v[184:187], v[52:55]
	v_mfma_f32_16x16x32_bf16 v[48:51], v[176:179], v[184:187], v[48:51]
	v_mfma_f32_16x16x32_bf16 v[36:39], v[168:171], v[192:195], v[36:39]
	v_mfma_f32_16x16x32_bf16 v[32:35], v[176:179], v[192:195], v[32:35]
	v_mfma_f32_16x16x32_bf16 v[20:23], v[168:171], v[200:203], v[20:23]
	v_mfma_f32_16x16x32_bf16 v[16:19], v[176:179], v[200:203], v[16:19]
	v_mfma_f32_16x16x32_bf16 v[4:7], v[168:171], v[208:211], v[4:7]
	v_mfma_f32_16x16x32_bf16 v[0:3], v[176:179], v[208:211], v[0:3]
	v_mfma_f32_16x16x32_bf16 v[52:55], v[172:175], v[188:191], v[52:55]
	v_mfma_f32_16x16x32_bf16 v[48:51], v[180:183], v[188:191], v[48:51]
	v_mfma_f32_16x16x32_bf16 v[36:39], v[172:175], v[196:199], v[36:39]
	v_mfma_f32_16x16x32_bf16 v[32:35], v[180:183], v[196:199], v[32:35]
	v_mfma_f32_16x16x32_bf16 v[20:23], v[172:175], v[204:207], v[20:23]
	v_mfma_f32_16x16x32_bf16 v[16:19], v[180:183], v[204:207], v[16:19]
	v_mfma_f32_16x16x32_bf16 v[4:7], v[172:175], v[212:215], v[4:7]
	v_mfma_f32_16x16x32_bf16 v[0:3], v[180:183], v[212:215], v[0:3]
	s_setprio 0
	s_add_i32 s59, s59, 2
	s_add_u32 s57, s57, 0x100
	s_addc_u32 s58, s58, 0
	s_add_u32 s28, s28, 0x100
	s_addc_u32 s29, s29, 0
	s_cmp_gt_u32 s59, 13
	s_barrier
	s_cbranch_scc0 .LBB0_1705
	s_and_b64 vcc, exec, s[16:17]
	s_cbranch_vccz .LBB0_1708
	s_barrier

.LBB0_1783:
	ds_read_b128 v[144:147], v151
	ds_read_b128 v[156:159], v151 offset:1024
	ds_read_b128 v[160:163], v151 offset:2048
	ds_read_b128 v[164:167], v151 offset:3072
	ds_read_b128 v[168:171], v152
	ds_read_b128 v[172:175], v152 offset:1024
	ds_read_b128 v[176:179], v152 offset:2048
	ds_read_b128 v[180:183], v152 offset:3072
	s_add_u32 s30, s28, 0xfff00080
	s_addc_u32 s31, s29, -1
	s_cmp_eq_u32 s58, 60
	s_cselect_b32 s37, s19, s31
	s_cselect_b32 s36, s25, s30
	s_cselect_b32 s31, s17, s57
	s_cselect_b32 s30, s55, s56
	v_lshl_add_u64 v[216:217], s[28:29], 0, v[136:137]
	s_add_i32 m0, s27, 0xc000
	ds_read_b128 v[184:187], v153
	ds_read_b128 v[188:191], v153 offset:1024
	ds_read_b128 v[192:195], v153 offset:2048
	ds_read_b128 v[196:199], v153 offset:3072
	ds_read_b128 v[200:203], v153 offset:4096
	ds_read_b128 v[204:207], v153 offset:5120
	ds_read_b128 v[208:211], v153 offset:6144
	ds_read_b128 v[212:215], v153 offset:7168
	global_load_lds_dwordx4 v[216:217], off
	v_lshl_add_u64 v[216:217], s[28:29], 0, v[138:139]
	s_add_i32 m0, s27, 0xe000
	s_nop 0
	global_load_lds_dwordx4 v[216:217], off
	s_waitcnt vmcnt(8)
	s_waitcnt lgkmcnt(0)
	s_barrier
	s_setprio 1
	s_waitcnt lgkmcnt(0)
	v_mfma_f32_16x16x32_bf16 v[124:127], v[144:147], v[184:187], v[124:127]
	v_mfma_f32_16x16x32_bf16 v[120:123], v[160:163], v[184:187], v[120:123]
	v_mfma_f32_16x16x32_bf16 v[108:111], v[144:147], v[192:195], v[108:111]
	v_mfma_f32_16x16x32_bf16 v[104:107], v[160:163], v[192:195], v[104:107]
	v_mfma_f32_16x16x32_bf16 v[92:95], v[144:147], v[200:203], v[92:95]
	v_mfma_f32_16x16x32_bf16 v[88:91], v[160:163], v[200:203], v[88:91]
	v_mfma_f32_16x16x32_bf16 v[76:79], v[144:147], v[208:211], v[76:79]
	v_mfma_f32_16x16x32_bf16 v[72:75], v[160:163], v[208:211], v[72:75]
	v_mfma_f32_16x16x32_bf16 v[124:127], v[156:159], v[188:191], v[124:127]
	v_mfma_f32_16x16x32_bf16 v[120:123], v[164:167], v[188:191], v[120:123]
	v_mfma_f32_16x16x32_bf16 v[108:111], v[156:159], v[196:199], v[108:111]
	v_mfma_f32_16x16x32_bf16 v[104:107], v[164:167], v[196:199], v[104:107]
	v_mfma_f32_16x16x32_bf16 v[92:95], v[156:159], v[204:207], v[92:95]
	v_mfma_f32_16x16x32_bf16 v[88:91], v[164:167], v[204:207], v[88:91]
	v_mfma_f32_16x16x32_bf16 v[76:79], v[156:159], v[212:215], v[76:79]
	v_mfma_f32_16x16x32_bf16 v[72:75], v[164:167], v[212:215], v[72:75]
	s_setprio 0
	s_setprio 1
	v_mfma_f32_16x16x32_bf16 v[116:119], v[168:171], v[184:187], v[116:119]
	v_mfma_f32_16x16x32_bf16 v[112:115], v[176:179], v[184:187], v[112:115]
	v_mfma_f32_16x16x32_bf16 v[100:103], v[168:171], v[192:195], v[100:103]
	v_mfma_f32_16x16x32_bf16 v[96:99], v[176:179], v[192:195], v[96:99]
	v_mfma_f32_16x16x32_bf16 v[84:87], v[168:171], v[200:203], v[84:87]
	v_mfma_f32_16x16x32_bf16 v[80:83], v[176:179], v[200:203], v[80:83]
	v_mfma_f32_16x16x32_bf16 v[68:71], v[168:171], v[208:211], v[68:71]
	v_mfma_f32_16x16x32_bf16 v[64:67], v[176:179], v[208:211], v[64:67]
	v_mfma_f32_16x16x32_bf16 v[116:119], v[172:175], v[188:191], v[116:119]
	v_mfma_f32_16x16x32_bf16 v[112:115], v[180:183], v[188:191], v[112:115]
	v_mfma_f32_16x16x32_bf16 v[100:103], v[172:175], v[196:199], v[100:103]
	v_mfma_f32_16x16x32_bf16 v[96:99], v[180:183], v[196:199], v[96:99]
	v_mfma_f32_16x16x32_bf16 v[84:87], v[172:175], v[204:207], v[84:87]
	v_mfma_f32_16x16x32_bf16 v[80:83], v[180:183], v[204:207], v[80:83]
	v_mfma_f32_16x16x32_bf16 v[68:71], v[172:175], v[212:215], v[68:71]
	v_mfma_f32_16x16x32_bf16 v[64:67], v[180:183], v[212:215], v[64:67]
	s_setprio 0
	s_barrier
	s_add_i32 s59, s53, s40
	v_lshl_add_u64 v[216:217], s[30:31], 0, v[130:131]
	s_mov_b32 m0, s59
	ds_read_b128 v[184:187], v153 offset:16384
	ds_read_b128 v[188:191], v153 offset:17408
	ds_read_b128 v[192:195], v153 offset:18432
	ds_read_b128 v[196:199], v153 offset:19456
	ds_read_b128 v[200:203], v153 offset:20480
	ds_read_b128 v[204:207], v153 offset:21504
	ds_read_b128 v[208:211], v153 offset:22528
	ds_read_b128 v[212:215], v153 offset:23552
	global_load_lds_dwordx4 v[216:217], off
	s_add_i32 m0, s59, 0x2000
	s_add_u32 s60, s30, 0x100000
	v_lshl_add_u64 v[218:219], s[30:31], 0, v[134:135]
	s_addc_u32 s61, s31, 0
	s_add_i32 s59, s54, s40
	global_load_lds_dwordx4 v[218:219], off
	v_lshl_add_u64 v[220:221], s[60:61], 0, v[130:131]
	s_mov_b32 m0, s59
	v_lshl_add_u64 v[222:223], s[36:37], 0, v[132:133]
	global_load_lds_dwordx4 v[220:221], off
	v_lshl_add_u64 v[220:221], s[60:61], 0, v[134:135]
	s_add_i32 m0, s59, 0x2000
	s_nop 0
	global_load_lds_dwordx4 v[220:221], off
	v_lshl_add_u64 v[220:221], s[36:37], 0, v[128:129]
	s_mov_b32 m0, s27
	s_nop 0
	global_load_lds_dwordx4 v[220:221], off
	s_mov_b32 m0, s41
	s_nop 0
	global_load_lds_dwordx4 v[222:223], off
	s_waitcnt vmcnt(8)
	s_waitcnt lgkmcnt(0)
	s_barrier
	s_setprio 1
	s_waitcnt lgkmcnt(0)
	v_mfma_f32_16x16x32_bf16 v[60:63], v[144:147], v[184:187], v[60:63]
	v_mfma_f32_16x16x32_bf16 v[56:59], v[160:163], v[184:187], v[56:59]
	v_mfma_f32_16x16x32_bf16 v[44:47], v[144:147], v[192:195], v[44:47]
	v_mfma_f32_16x16x32_bf16 v[40:43], v[160:163], v[192:195], v[40:43]
	v_mfma_f32_16x16x32_bf16 v[28:31], v[144:147], v[200:203], v[28:31]
	v_mfma_f32_16x16x32_bf16 v[24:27], v[160:163], v[200:203], v[24:27]
	v_mfma_f32_16x16x32_bf16 v[12:15], v[144:147], v[208:211], v[12:15]
	v_mfma_f32_16x16x32_bf16 v[8:11], v[160:163], v[208:211], v[8:11]
	v_mfma_f32_16x16x32_bf16 v[60:63], v[156:159], v[188:191], v[60:63]
	v_mfma_f32_16x16x32_bf16 v[56:59], v[164:167], v[188:191], v[56:59]
	v_mfma_f32_16x16x32_bf16 v[44:47], v[156:159], v[196:199], v[44:47]
	v_mfma_f32_16x16x32_bf16 v[40:43], v[164:167], v[196:199], v[40:43]
	v_mfma_f32_16x16x32_bf16 v[28:31], v[156:159], v[204:207], v[28:31]
	v_mfma_f32_16x16x32_bf16 v[24:27], v[164:167], v[204:207], v[24:27]
	v_mfma_f32_16x16x32_bf16 v[12:15], v[156:159], v[212:215], v[12:15]
	v_mfma_f32_16x16x32_bf16 v[8:11], v[164:167], v[212:215], v[8:11]
	s_setprio 0
	s_setprio 1
	v_mfma_f32_16x16x32_bf16 v[52:55], v[168:171], v[184:187], v[52:55]
	v_mfma_f32_16x16x32_bf16 v[48:51], v[176:179], v[184:187], v[48:51]
	v_mfma_f32_16x16x32_bf16 v[36:39], v[168:171], v[192:195], v[36:39]
	v_mfma_f32_16x16x32_bf16 v[32:35], v[176:179], v[192:195], v[32:35]
	v_mfma_f32_16x16x32_bf16 v[20:23], v[168:171], v[200:203], v[20:23]
	v_mfma_f32_16x16x32_bf16 v[16:19], v[176:179], v[200:203], v[16:19]
	v_mfma_f32_16x16x32_bf16 v[4:7], v[168:171], v[208:211], v[4:7]
	v_mfma_f32_16x16x32_bf16 v[0:3], v[176:179], v[208:211], v[0:3]
	v_mfma_f32_16x16x32_bf16 v[52:55], v[172:175], v[188:191], v[52:55]
	v_mfma_f32_16x16x32_bf16 v[48:51], v[180:183], v[188:191], v[48:51]
	v_mfma_f32_16x16x32_bf16 v[36:39], v[172:175], v[196:199], v[36:39]
	v_mfma_f32_16x16x32_bf16 v[32:35], v[180:183], v[196:199], v[32:35]
	v_mfma_f32_16x16x32_bf16 v[20:23], v[172:175], v[204:207], v[20:23]
	v_mfma_f32_16x16x32_bf16 v[16:19], v[180:183], v[204:207], v[16:19]
	v_mfma_f32_16x16x32_bf16 v[4:7], v[172:175], v[212:215], v[4:7]
	v_mfma_f32_16x16x32_bf16 v[0:3], v[180:183], v[212:215], v[0:3]
	s_setprio 0
	s_barrier
	s_add_i32 s59, 0, 0x18000
	v_add_u32_e32 v155, s59, v149
	s_add_i32 s60, 0, 0x1c000
	ds_read_b128 v[144:147], v155
	ds_read_b128 v[156:159], v155 offset:1024
	ds_read_b128 v[160:163], v155 offset:2048
	ds_read_b128 v[164:167], v155 offset:3072
	v_add_u32_e32 v155, s60, v149
	ds_read_b128 v[168:171], v155
	ds_read_b128 v[172:175], v155 offset:1024
	ds_read_b128 v[176:179], v155 offset:2048
	ds_read_b128 v[180:183], v155 offset:3072
	s_add_u32 s36, s36, 0x100000
	s_addc_u32 s37, s37, 0
	s_mov_b32 m0, s42
	v_lshl_add_u64 v[224:225], s[36:37], 0, v[128:129]
	ds_read_b128 v[184:187], v153 offset:32768
	ds_read_b128 v[188:191], v153 offset:33792
	ds_read_b128 v[192:195], v153 offset:34816
	ds_read_b128 v[196:199], v153 offset:35840
	ds_read_b128 v[200:203], v153 offset:36864
	ds_read_b128 v[204:207], v153 offset:37888
	ds_read_b128 v[208:211], v153 offset:38912
	ds_read_b128 v[212:215], v153 offset:39936
	global_load_lds_dwordx4 v[224:225], off
	v_lshl_add_u64 v[224:225], s[36:37], 0, v[132:133]
	s_mov_b32 m0, s43
	s_nop 0
	global_load_lds_dwordx4 v[224:225], off
	s_waitcnt vmcnt(8)
	s_waitcnt lgkmcnt(0)
	s_barrier
	s_setprio 1
	s_waitcnt lgkmcnt(0)
	v_mfma_f32_16x16x32_bf16 v[124:127], v[144:147], v[184:187], v[124:127]
	v_mfma_f32_16x16x32_bf16 v[120:123], v[160:163], v[184:187], v[120:123]
	v_mfma_f32_16x16x32_bf16 v[108:111], v[144:147], v[192:195], v[108:111]
	v_mfma_f32_16x16x32_bf16 v[104:107], v[160:163], v[192:195], v[104:107]
	v_mfma_f32_16x16x32_bf16 v[92:95], v[144:147], v[200:203], v[92:95]
	v_mfma_f32_16x16x32_bf16 v[88:91], v[160:163], v[200:203], v[88:91]
	v_mfma_f32_16x16x32_bf16 v[76:79], v[144:147], v[208:211], v[76:79]
	v_mfma_f32_16x16x32_bf16 v[72:75], v[160:163], v[208:211], v[72:75]
	v_mfma_f32_16x16x32_bf16 v[124:127], v[156:159], v[188:191], v[124:127]
	v_mfma_f32_16x16x32_bf16 v[120:123], v[164:167], v[188:191], v[120:123]
	v_mfma_f32_16x16x32_bf16 v[108:111], v[156:159], v[196:199], v[108:111]
	v_mfma_f32_16x16x32_bf16 v[104:107], v[164:167], v[196:199], v[104:107]
	v_mfma_f32_16x16x32_bf16 v[92:95], v[156:159], v[204:207], v[92:95]
	v_mfma_f32_16x16x32_bf16 v[88:91], v[164:167], v[204:207], v[88:91]
	v_mfma_f32_16x16x32_bf16 v[76:79], v[156:159], v[212:215], v[76:79]
	v_mfma_f32_16x16x32_bf16 v[72:75], v[164:167], v[212:215], v[72:75]
	s_setprio 0
	s_setprio 1
	v_mfma_f32_16x16x32_bf16 v[116:119], v[168:171], v[184:187], v[116:119]
	v_mfma_f32_16x16x32_bf16 v[112:115], v[176:179], v[184:187], v[112:115]
	v_mfma_f32_16x16x32_bf16 v[100:103], v[168:171], v[192:195], v[100:103]
	v_mfma_f32_16x16x32_bf16 v[96:99], v[176:179], v[192:195], v[96:99]
	v_mfma_f32_16x16x32_bf16 v[84:87], v[168:171], v[200:203], v[84:87]
	v_mfma_f32_16x16x32_bf16 v[80:83], v[176:179], v[200:203], v[80:83]
	v_mfma_f32_16x16x32_bf16 v[68:71], v[168:171], v[208:211], v[68:71]
	v_mfma_f32_16x16x32_bf16 v[64:67], v[176:179], v[208:211], v[64:67]
	v_mfma_f32_16x16x32_bf16 v[116:119], v[172:175], v[188:191], v[116:119]
	v_mfma_f32_16x16x32_bf16 v[112:115], v[180:183], v[188:191], v[112:115]
	v_mfma_f32_16x16x32_bf16 v[100:103], v[172:175], v[196:199], v[100:103]
	v_mfma_f32_16x16x32_bf16 v[96:99], v[180:183], v[196:199], v[96:99]
	v_mfma_f32_16x16x32_bf16 v[84:87], v[172:175], v[204:207], v[84:87]
	v_mfma_f32_16x16x32_bf16 v[80:83], v[180:183], v[204:207], v[80:83]
	v_mfma_f32_16x16x32_bf16 v[68:71], v[172:175], v[212:215], v[68:71]
	v_mfma_f32_16x16x32_bf16 v[64:67], v[180:183], v[212:215], v[64:67]
	s_setprio 0
	s_barrier
	s_add_i32 s36, s59, s40
	v_lshl_add_u64 v[216:217], v[216:217], 0, s[12:13]
	s_mov_b32 m0, s36
	ds_read_b128 v[184:187], v153 offset:49152
	ds_read_b128 v[188:191], v153 offset:50176
	ds_read_b128 v[192:195], v153 offset:51200
	ds_read_b128 v[196:199], v153 offset:52224
	ds_read_b128 v[200:203], v153 offset:53248
	ds_read_b128 v[204:207], v153 offset:54272
	ds_read_b128 v[208:211], v153 offset:55296
	ds_read_b128 v[212:215], v153 offset:56320
	global_load_lds_dwordx4 v[216:217], off
	s_add_i32 m0, s36, 0x2000
	s_add_u32 s30, s30, 0x100080
	v_lshl_add_u64 v[216:217], v[218:219], 0, s[12:13]
	s_addc_u32 s31, s31, 0
	s_add_i32 s36, s60, s40
	global_load_lds_dwordx4 v[216:217], off
	v_lshl_add_u64 v[216:217], s[30:31], 0, v[130:131]
	s_mov_b32 m0, s36
	s_nop 0
	global_load_lds_dwordx4 v[216:217], off
	v_lshl_add_u64 v[216:217], s[30:31], 0, v[134:135]
	s_add_i32 m0, s36, 0x2000
	s_nop 0
	global_load_lds_dwordx4 v[216:217], off
	v_lshl_add_u64 v[216:217], v[220:221], 0, s[12:13]
	s_mov_b32 m0, s45
	s_nop 0
	global_load_lds_dwordx4 v[216:217], off
	v_lshl_add_u64 v[216:217], v[222:223], 0, s[12:13]
	s_mov_b32 m0, s46
	s_nop 0
	global_load_lds_dwordx4 v[216:217], off
	s_waitcnt vmcnt(8)
	s_waitcnt lgkmcnt(0)
	s_barrier
	s_setprio 1
	s_waitcnt lgkmcnt(0)
	v_mfma_f32_16x16x32_bf16 v[60:63], v[144:147], v[184:187], v[60:63]
	v_mfma_f32_16x16x32_bf16 v[56:59], v[160:163], v[184:187], v[56:59]
	v_mfma_f32_16x16x32_bf16 v[44:47], v[144:147], v[192:195], v[44:47]
	v_mfma_f32_16x16x32_bf16 v[40:43], v[160:163], v[192:195], v[40:43]
	v_mfma_f32_16x16x32_bf16 v[28:31], v[144:147], v[200:203], v[28:31]
	v_mfma_f32_16x16x32_bf16 v[24:27], v[160:163], v[200:203], v[24:27]
	v_mfma_f32_16x16x32_bf16 v[12:15], v[144:147], v[208:211], v[12:15]
	v_mfma_f32_16x16x32_bf16 v[8:11], v[160:163], v[208:211], v[8:11]
	v_mfma_f32_16x16x32_bf16 v[60:63], v[156:159], v[188:191], v[60:63]
	v_mfma_f32_16x16x32_bf16 v[56:59], v[164:167], v[188:191], v[56:59]
	v_mfma_f32_16x16x32_bf16 v[44:47], v[156:159], v[196:199], v[44:47]
	v_mfma_f32_16x16x32_bf16 v[40:43], v[164:167], v[196:199], v[40:43]
	v_mfma_f32_16x16x32_bf16 v[28:31], v[156:159], v[204:207], v[28:31]
	v_mfma_f32_16x16x32_bf16 v[24:27], v[164:167], v[204:207], v[24:27]
	v_mfma_f32_16x16x32_bf16 v[12:15], v[156:159], v[212:215], v[12:15]
	v_mfma_f32_16x16x32_bf16 v[8:11], v[164:167], v[212:215], v[8:11]
	s_setprio 0
	s_setprio 1
	v_mfma_f32_16x16x32_bf16 v[52:55], v[168:171], v[184:187], v[52:55]
	v_mfma_f32_16x16x32_bf16 v[48:51], v[176:179], v[184:187], v[48:51]
	v_mfma_f32_16x16x32_bf16 v[36:39], v[168:171], v[192:195], v[36:39]
	v_mfma_f32_16x16x32_bf16 v[32:35], v[176:179], v[192:195], v[32:35]
	v_mfma_f32_16x16x32_bf16 v[20:23], v[168:171], v[200:203], v[20:23]
	v_mfma_f32_16x16x32_bf16 v[16:19], v[176:179], v[200:203], v[16:19]
	v_mfma_f32_16x16x32_bf16 v[4:7], v[168:171], v[208:211], v[4:7]
	v_mfma_f32_16x16x32_bf16 v[0:3], v[176:179], v[208:211], v[0:3]
	v_mfma_f32_16x16x32_bf16 v[52:55], v[172:175], v[188:191], v[52:55]
	v_mfma_f32_16x16x32_bf16 v[48:51], v[180:183], v[188:191], v[48:51]
	v_mfma_f32_16x16x32_bf16 v[36:39], v[172:175], v[196:199], v[36:39]
	v_mfma_f32_16x16x32_bf16 v[32:35], v[180:183], v[196:199], v[32:35]
	v_mfma_f32_16x16x32_bf16 v[20:23], v[172:175], v[204:207], v[20:23]
	v_mfma_f32_16x16x32_bf16 v[16:19], v[180:183], v[204:207], v[16:19]
	v_mfma_f32_16x16x32_bf16 v[4:7], v[172:175], v[212:215], v[4:7]
	v_mfma_f32_16x16x32_bf16 v[0:3], v[180:183], v[212:215], v[0:3]
	s_setprio 0
	s_add_i32 s58, s58, 2
	s_add_u32 s56, s56, 0x100
	s_addc_u32 s57, s57, 0
	s_add_u32 s28, s28, 0x100
	s_addc_u32 s29, s29, 0
	s_cmp_gt_u32 s58, 61
	s_barrier
	s_cbranch_scc0 .LBB0_1783
	s_and_b64 vcc, exec, s[14:15]
	s_cbranch_vccz .LBB0_1786
	s_barrier
